# S5 table builder (ef_item): remaining c_re/c_im load pairs issued together instead of one round trip per store
# speedup vs baseline: 1.0190x; 1.0002x over previous
; DEV int get_tid() { int t; asm volatile("v_mov_b32 %0, %1" : "=v"(t) : "v"((int)(threadIdx.x & 255))); return t; }
; DEV unsigned pk_bf16(float lo, float hi) { unsigned r; asm("v_cvt_pk_bf16_f32 %0, %1, %2" : "=v"(r) : "v"(lo), "v"(hi)); return r; }
; DEV float2 cmulf(float2 a, float2 b) { return make_float2(a.x * b.x - a.y * b.y, a.x * b.y + a.y * b.x); }
; DEV Disc s5_disc(const P& p, int l, int dir, int g, int pp) {
;   Disc d; const int gi = (l * 2 + dir) * 32 + g;
;   d.dt = (double)expf(p.log_dt[gi]); d.are = p.a_re[gi * 64 + pp]; d.aim = p.a_im[gi * 64 + pp];
;   const float mag = __expf((float)(d.dt * (double)d.are)); float sn, cs; sincos_d(d.dt * (double)d.aim, sn, cs);
;   const float abr = mag * cs, abi = mag * sn, den = d.are * d.are + d.aim * d.aim, nr = abr - 1.0f, ni = abi;
;   d.fre = (nr * d.are + ni * d.aim) / den; d.fim = (ni * d.are - nr * d.aim) / den;
;   return d;
; }
; DEV float2 cpow(const Disc& d, int e) {
;   const float mag = __expf((float)((double)e * d.dt * (double)d.are)); float sn, cs; sincos_d((double)e * d.dt * (double)d.aim, sn, cs);
;   return make_float2(mag * cs, mag * sn);
; }
; DEV void ef_item(const P& p, int l, int it) {
;   const int g = it >> 4, id = (it & 15) * 256 + get_tid();
;   const int t = id & 31, pp = (id >> 5) & 63, dir = id >> 11, gi = (l * 2 + dir) * 32 + g;
;   const Disc d = s5_disc(p, l, dir, g, pp);
;   const float2 we = cpow(d, dir == 0 ? t + 1 : 32 - t), wf = cpow(d, dir == 0 ? 31 - t : t);
;   unsigned* Et = (unsigned*)(p.ws + OFF_ET) + (size_t)g * 512 * 128;
;   bf16_t* Ft = (bf16_t*)(p.ws + OFF_FT) + (size_t)g * 256 * 512;
; #pragma unroll
;   for (int c = 0; c < 16; ++c) {
;     const float2 cc = make_float2(p.c_re[((size_t)gi * 16 + c) * 64 + pp], p.c_im[((size_t)gi * 16 + c) * 64 + pp]);
;     const float2 cw = cmulf(cc, we);
;     Et[(size_t)(t * 16 + c) * 128 + dir * 64 + pp] = pk_bf16(cw.x, -cw.y);
;   }
.LBB0_96:
	s_and_b32 s5, s8, 0xf00
	v_mov_b32 v19, v238
	s_ashr_i32 s4, s10, 4
	v_add_u32_e32 v12, s5, v19
	v_ashrrev_i32_e32 v18, 11, v12
	v_lshlrev_b32_e32 v0, 5, v18
	v_ashrrev_i32_e32 v1, 31, v0
	s_ashr_i32 s5, s4, 31
	v_add3_u32 v4, s4, 64, v0
	v_lshl_add_u64 v[0:1], s[4:5], 0, v[0:1]
	v_lshl_add_u64 v[0:1], v[0:1], 2, s[44:45]
	global_load_dword v0, v[0:1], off offset:256
	v_bfe_u32 v17, v12, 5, 6
	v_and_b32_e32 v16, 31, v19
	v_ashrrev_i32_e32 v5, 31, v4
	s_lshl_b64 s[4:5], s[4:5], 18
	s_add_u32 s12, s2, s4
	s_addc_u32 s13, s3, s5
	v_lshlrev_b32_e32 v40, 2, v17
	s_add_u32 s4, s6, s4
	s_addc_u32 s5, s7, s5
	s_add_i32 s10, s10, s79
	s_add_i32 s8, s8, s9
	s_cmpk_lt_i32 s10, 0x200
	s_waitcnt vmcnt(0)
	v_mul_f32_e32 v1, 0x3fb8aa3b, v0
	v_fma_f32 v2, v0, s34, -v1
	v_rndne_f32_e32 v3, v1
	v_fmac_f32_e32 v2, 0x32a5705f, v0
	v_sub_f32_e32 v1, v1, v3
	v_add_f32_e32 v1, v1, v2
	v_exp_f32_e32 v1, v1
	v_cvt_i32_f32_e32 v2, v3
	v_cmp_ngt_f32_e32 vcc, s35, v0
	v_ldexp_f32 v1, v1, v2
	s_nop 0
	v_cndmask_b32_e32 v1, 0, v1, vcc
	v_cmp_nlt_f32_e32 vcc, s36, v0
	v_lshl_or_b32 v0, v4, 6, v17
	v_lshlrev_b64 v[4:5], 10, v[4:5]
	v_cndmask_b32_e32 v8, v236, v1, vcc
	v_ashrrev_i32_e32 v1, 31, v0
	v_lshlrev_b64 v[2:3], 2, v[0:1]
	v_lshl_add_u64 v[0:1], s[40:41], 0, v[2:3]
	global_load_dword v0, v[0:1], off
	v_lshl_add_u64 v[2:3], s[42:43], 0, v[2:3]
	global_load_dword v1, v[2:3], off
	v_cvt_f64_f32_e32 v[6:7], v8
	v_cmp_gt_u32_e32 vcc, s14, v12
	s_waitcnt vmcnt(1)
	v_mul_f32_e32 v2, v8, v0
	v_mul_f32_e32 v2, 0x3fb8aa3b, v2
	s_waitcnt vmcnt(0)
	v_cvt_f64_f32_e32 v[8:9], v1
	v_exp_f32_e32 v13, v2
	v_mul_f64 v[2:3], v[6:7], v[8:9]
	v_mul_f64 v[10:11], v[2:3], s[28:29]
	v_rndne_f64_e32 v[10:11], v[10:11]
	v_fmac_f64_e32 v[2:3], s[30:31], v[10:11]
	v_mul_f64 v[2:3], v[2:3], s[28:29]
	v_cvt_f32_f64_e32 v2, v[2:3]
	v_sin_f32_e32 v3, v2
	v_cos_f32_e32 v10, v2
	v_sub_u32_e32 v11, 32, v16
	v_mul_f32_e32 v2, v13, v3
	v_fma_f32 v3, v13, v10, -1.0
	v_add_u32_e32 v10, 1, v16
	v_cndmask_b32_e32 v10, v11, v10, vcc
	v_cvt_f64_u32_e32 v[10:11], v10
	v_mul_f64 v[12:13], v[6:7], v[10:11]
	v_cvt_f64_f32_e32 v[10:11], v0
	v_mul_f64 v[14:15], v[12:13], v[10:11]
	v_cvt_f32_f64_e32 v14, v[14:15]
	v_mul_f32_e32 v14, 0x3fb8aa3b, v14
	v_mul_f64 v[12:13], v[12:13], v[8:9]
	v_exp_f32_e32 v20, v14
	v_mul_f64 v[14:15], v[12:13], s[28:29]
	v_rndne_f64_e32 v[14:15], v[14:15]
	v_fmac_f64_e32 v[12:13], s[30:31], v[14:15]
	v_bitop3_b32 v14, v19, 31, v19 bitop3:0xc
	v_cndmask_b32_e32 v14, v16, v14, vcc
	v_cvt_f64_u32_e32 v[14:15], v14
	v_mul_f64 v[12:13], v[12:13], s[28:29]
	v_mul_f64 v[14:15], v[6:7], v[14:15]
	v_cvt_f32_f64_e32 v12, v[12:13]
	v_mul_f64 v[8:9], v[14:15], v[8:9]
	v_sin_f32_e32 v13, v12
	v_cos_f32_e32 v12, v12
	v_mul_f64 v[6:7], v[14:15], v[10:11]
	v_mul_f64 v[10:11], v[8:9], s[28:29]
	v_rndne_f64_e32 v[10:11], v[10:11]
	v_fmac_f64_e32 v[8:9], s[30:31], v[10:11]
	v_or_b32_e32 v10, v4, v17
	v_mov_b32_e32 v11, v5
	v_lshlrev_b64 v[10:11], 2, v[10:11]
	v_mul_f32_e32 v12, v20, v12
	v_mul_f32_e32 v13, v20, v13
	v_lshl_add_u64 v[20:21], s[50:51], 0, v[10:11]
	v_lshl_add_u64 v[10:11], s[0:1], 0, v[10:11]
	v_mul_f64 v[8:9], v[8:9], s[28:29]
	global_load_dword v19, v[10:11], off
	v_cvt_f32_f64_e32 v6, v[6:7]
	v_cvt_f32_f64_e32 v7, v[8:9]
	global_load_dword v9, v[20:21], off
	v_lshlrev_b32_e32 v14, 6, v18
	v_ashrrev_i32_e32 v15, 31, v14
	v_lshl_add_u64 v[14:15], v[14:15], 2, s[12:13]
	v_lshl_add_u64 v[14:15], v[14:15], 0, v[40:41]
	v_lshlrev_b32_e32 v40, 13, v16
	v_lshl_add_u64 v[14:15], v[14:15], 0, v[40:41]
	v_lshl_or_b32 v4, v17, 4, v4
	v_lshlrev_b64 v[4:5], 2, v[4:5]
	v_lshl_add_u64 v[26:27], s[48:49], 0, v[4:5]
	v_lshl_add_u64 v[24:25], s[46:47], 0, v[4:5]
	v_mov_b32_e32 v4, v1
	v_pk_mul_f32 v[4:5], v[4:5], v[2:3] op_sel:[0,1] op_sel_hi:[0,0]
	v_pk_fma_f32 v[28:29], v[0:1], v[2:3], v[4:5] neg_lo:[0,0,1] neg_hi:[0,0,1]
	v_cos_f32_e32 v8, v7
	v_mul_f32_e32 v6, 0x3fb8aa3b, v6
	v_exp_f32_e32 v6, v6
	v_lshlrev_b32_e32 v18, 7, v18
	v_lshl_or_b32 v18, v17, 1, v18
	v_lshlrev_b32_e32 v40, 5, v16
	s_waitcnt vmcnt(1)
	v_mul_f32_e32 v22, v19, v13
	v_mul_f32_e32 v19, v19, v12
	s_waitcnt vmcnt(0)
	v_fmac_f32_e32 v19, v9, v13
	v_fma_f32 v22, v9, v12, -v22
	v_xor_b32_e32 v9, 0x80000000, v19
	v_cvt_pk_bf16_f32 v9, v22, v9
	global_store_dword v[14:15], v9, off
	global_load_dword v102, v[20:21], off offset:256
	global_load_dword v103, v[10:11], off offset:256
	global_load_dword v104, v[20:21], off offset:512
	global_load_dword v105, v[10:11], off offset:512
	global_load_dword v106, v[20:21], off offset:768
	global_load_dword v107, v[10:11], off offset:768
	global_load_dword v108, v[20:21], off offset:1024
	global_load_dword v109, v[10:11], off offset:1024
	global_load_dword v110, v[20:21], off offset:1280
	global_load_dword v111, v[10:11], off offset:1280
	global_load_dword v112, v[20:21], off offset:1536
	global_load_dword v113, v[10:11], off offset:1536
	global_load_dword v114, v[20:21], off offset:1792
	global_load_dword v115, v[10:11], off offset:1792
	global_load_dword v116, v[20:21], off offset:2048
	global_load_dword v117, v[10:11], off offset:2048
	global_load_dword v118, v[20:21], off offset:2304
	global_load_dword v119, v[10:11], off offset:2304
	global_load_dword v120, v[20:21], off offset:2560
	global_load_dword v121, v[10:11], off offset:2560
	global_load_dword v122, v[20:21], off offset:2816
	global_load_dword v123, v[10:11], off offset:2816
	global_load_dword v124, v[20:21], off offset:3072
	global_load_dword v125, v[10:11], off offset:3072
	global_load_dword v126, v[20:21], off offset:3328
	global_load_dword v127, v[10:11], off offset:3328
	global_load_dword v128, v[20:21], off offset:3584
	global_load_dword v129, v[10:11], off offset:3584
	global_load_dword v130, v[20:21], off offset:3840
	global_load_dword v131, v[10:11], off offset:3840
	s_waitcnt vmcnt(28)
; DEV unsigned pk_bf16(float lo, float hi) { unsigned r; asm("v_cvt_pk_bf16_f32 %0, %1, %2" : "=v"(r) : "v"(lo), "v"(hi)); return r; }
; DEV float2 cmulf(float2 a, float2 b) { return make_float2(a.x * b.x - a.y * b.y, a.x * b.y + a.y * b.x); }
; DEV Disc s5_disc(const P& p, int l, int dir, int g, int pp) {
;     ...
;   const float abr = mag * cs, abi = mag * sn, den = d.are * d.are + d.aim * d.aim, nr = abr - 1.0f, ni = abi;
;   d.fre = (nr * d.are + ni * d.aim) / den; d.fim = (ni * d.are - nr * d.aim) / den;
; DEV void ef_item(const P& p, int l, int it) {
;     ...
;   for (int c = 0; c < 16; ++c) {
;     const float2 cc = make_float2(p.c_re[((size_t)gi * 16 + c) * 64 + pp], p.c_im[((size_t)gi * 16 + c) * 64 + pp]);
;     const float2 cw = cmulf(cc, we);
;     Et[(size_t)(t * 16 + c) * 128 + dir * 64 + pp] = pk_bf16(cw.x, -cw.y);
;   }
;   const float2 f = make_float2(d.fre, d.fim);
;   unsigned fr[8], fi[8];
; #pragma unroll
;   for (int c2 = 0; c2 < 8; ++c2) {
;     const size_t bi = ((size_t)gi * 64 + pp) * 16 + c2 * 2;
;     const float2 v0 = cmulf(wf, cmulf(f, make_float2(p.b_re[bi], p.b_im[bi])));
;     const float2 v1 = cmulf(wf, cmulf(f, make_float2(p.b_re[bi + 1], p.b_im[bi + 1])));
;     fr[c2] = pk_bf16(v0.x, v1.x); fi[c2] = pk_bf16(v0.y, v1.y);
	v_mul_f32_e32 v22, v103, v13
	v_mul_f32_e32 v19, v103, v12
	v_fmac_f32_e32 v19, v102, v13
	v_fma_f32 v22, v102, v12, -v22
	v_xor_b32_e32 v9, 0x80000000, v19
	v_cvt_pk_bf16_f32 v9, v22, v9
	global_store_dword v[14:15], v9, off offset:512
	s_waitcnt vmcnt(27)
	v_mul_f32_e32 v22, v105, v13
	v_mul_f32_e32 v19, v105, v12
	v_fmac_f32_e32 v19, v104, v13
	v_fma_f32 v22, v104, v12, -v22
	v_xor_b32_e32 v9, 0x80000000, v19
	v_cvt_pk_bf16_f32 v9, v22, v9
	global_store_dword v[14:15], v9, off offset:1024
	s_waitcnt vmcnt(26)
	v_mul_f32_e32 v22, v13, v107
	v_mul_f32_e32 v19, v12, v107
	v_fmac_f32_e32 v19, v13, v106
	v_fma_f32 v22, v12, v106, -v22
	v_xor_b32_e32 v9, 0x80000000, v19
	v_cvt_pk_bf16_f32 v9, v22, v9
	global_store_dword v[14:15], v9, off offset:1536
	s_waitcnt vmcnt(25)
	v_mul_f32_e32 v22, v13, v109
	v_mul_f32_e32 v19, v12, v109
	v_fmac_f32_e32 v19, v13, v108
	v_fma_f32 v22, v12, v108, -v22
	v_xor_b32_e32 v9, 0x80000000, v19
	v_cvt_pk_bf16_f32 v9, v22, v9
	global_store_dword v[14:15], v9, off offset:2048
	s_waitcnt vmcnt(24)
	v_mul_f32_e32 v22, v13, v111
	v_mul_f32_e32 v19, v12, v111
	v_fmac_f32_e32 v19, v13, v110
	v_fma_f32 v22, v12, v110, -v22
	v_xor_b32_e32 v9, 0x80000000, v19
	v_cvt_pk_bf16_f32 v9, v22, v9
	global_store_dword v[14:15], v9, off offset:2560
	s_waitcnt vmcnt(23)
	v_mul_f32_e32 v22, v13, v113
	v_mul_f32_e32 v19, v12, v113
	v_fmac_f32_e32 v19, v13, v112
	v_fma_f32 v22, v12, v112, -v22
	v_xor_b32_e32 v9, 0x80000000, v19
	v_cvt_pk_bf16_f32 v9, v22, v9
	global_store_dword v[14:15], v9, off offset:3072
	s_waitcnt vmcnt(22)
	v_mul_f32_e32 v22, v13, v115
	v_mul_f32_e32 v19, v12, v115
	v_fmac_f32_e32 v19, v13, v114
	v_fma_f32 v22, v12, v114, -v22
	v_xor_b32_e32 v9, 0x80000000, v19
	v_cvt_pk_bf16_f32 v9, v22, v9
	global_store_dword v[14:15], v9, off offset:3584
	v_add_co_u32_e32 v14, vcc, s11, v14
	s_waitcnt vmcnt(21)
	v_mul_f32_e32 v22, v13, v117
	v_mul_f32_e32 v19, v12, v117
	v_fmac_f32_e32 v19, v13, v116
	v_fma_f32 v22, v12, v116, -v22
	v_xor_b32_e32 v9, 0x80000000, v19
	v_addc_co_u32_e32 v15, vcc, 0, v15, vcc
	v_cvt_pk_bf16_f32 v9, v22, v9
	global_store_dword v[14:15], v9, off
	s_waitcnt vmcnt(20)
	v_mul_f32_e32 v22, v13, v119
	v_mul_f32_e32 v19, v12, v119
	v_fmac_f32_e32 v19, v13, v118
	v_fma_f32 v22, v12, v118, -v22
	v_xor_b32_e32 v9, 0x80000000, v19
	v_cvt_pk_bf16_f32 v9, v22, v9
	global_store_dword v[14:15], v9, off offset:512
	s_waitcnt vmcnt(19)
	v_mul_f32_e32 v22, v13, v121
	v_mul_f32_e32 v19, v12, v121
	v_fmac_f32_e32 v19, v13, v120
	v_fma_f32 v22, v12, v120, -v22
	v_xor_b32_e32 v9, 0x80000000, v19
	v_cvt_pk_bf16_f32 v9, v22, v9
	global_store_dword v[14:15], v9, off offset:1024
	s_waitcnt vmcnt(18)
	v_mul_f32_e32 v22, v13, v123
	v_mul_f32_e32 v19, v12, v123
	v_fmac_f32_e32 v19, v13, v122
	v_fma_f32 v22, v12, v122, -v22
	v_xor_b32_e32 v9, 0x80000000, v19
	v_cvt_pk_bf16_f32 v9, v22, v9
	global_store_dword v[14:15], v9, off offset:1536
	s_waitcnt vmcnt(17)
	v_mul_f32_e32 v22, v13, v125
	v_mul_f32_e32 v19, v12, v125
	v_fmac_f32_e32 v19, v13, v124
	v_fma_f32 v22, v12, v124, -v22
	v_xor_b32_e32 v9, 0x80000000, v19
	v_cvt_pk_bf16_f32 v9, v22, v9
	global_store_dword v[14:15], v9, off offset:2048
	s_waitcnt vmcnt(16)
	v_mul_f32_e32 v22, v13, v127
	v_mul_f32_e32 v19, v12, v127
	v_fmac_f32_e32 v19, v13, v126
	v_fma_f32 v22, v12, v126, -v22
	v_xor_b32_e32 v9, 0x80000000, v19
	v_cvt_pk_bf16_f32 v9, v22, v9
	global_store_dword v[14:15], v9, off offset:2560
	s_waitcnt vmcnt(15)
	v_mul_f32_e32 v22, v13, v129
	v_mul_f32_e32 v19, v12, v129
	v_fmac_f32_e32 v19, v13, v128
	v_fma_f32 v22, v12, v128, -v22
	v_xor_b32_e32 v9, 0x80000000, v19
	v_cvt_pk_bf16_f32 v9, v22, v9
	global_store_dword v[14:15], v9, off offset:3072
	s_waitcnt vmcnt(14)
	v_mul_f32_e32 v11, v13, v131
	v_mul_f32_e32 v10, v12, v131
	v_fmac_f32_e32 v10, v13, v130
	v_fma_f32 v11, v12, v130, -v11
	v_xor_b32_e32 v9, 0x80000000, v10
	v_cvt_pk_bf16_f32 v9, v11, v9
	global_store_dword v[14:15], v9, off offset:3584
	global_load_dwordx4 v[20:23], v[26:27], off
	global_load_dwordx4 v[10:13], v[24:25], off
	v_pk_mul_f32 v[14:15], v[0:1], v[0:1]
	v_pk_fma_f32 v[0:1], v[0:1], v[2:3], v[4:5] op_sel_hi:[0,1,1]
	v_pk_add_f32 v[2:3], v[14:15], v[14:15] op_sel:[0,1] op_sel_hi:[0,1]
	v_div_scale_f32 v0, s[12:13], v3, v3, v1
	v_rcp_f32_e32 v4, v0
	v_sin_f32_e32 v9, v7
	v_fma_f32 v5, -v0, v4, 1.0
	v_fmac_f32_e32 v4, v5, v4
	v_div_scale_f32 v5, vcc, v1, v3, v1
	v_mul_f32_e32 v7, v5, v4
	v_fma_f32 v14, -v0, v7, v5
	v_fmac_f32_e32 v7, v14, v4
	v_fma_f32 v0, -v0, v7, v5
	v_div_fmas_f32 v0, v0, v4, v7
	v_div_fixup_f32 v29, v0, v3, v1
	v_div_scale_f32 v0, s[12:13], v2, v2, v28
	v_rcp_f32_e32 v1, v0
	v_pk_mul_f32 v[30:31], v[6:7], v[8:9] op_sel_hi:[0,1]
	v_fma_f32 v3, -v0, v1, 1.0
	v_fmac_f32_e32 v1, v3, v1
	v_div_scale_f32 v3, vcc, v28, v2, v28
	v_mul_f32_e32 v4, v3, v1
	v_fma_f32 v5, -v0, v4, v3
	v_fmac_f32_e32 v4, v5, v1
	v_fma_f32 v0, -v0, v4, v3
	v_div_fmas_f32 v0, v0, v1, v4
	v_div_fixup_f32 v28, v0, v2, v28
	s_waitcnt vmcnt(1)
	v_pk_mul_f32 v[0:1], v[28:29], v[20:21] op_sel:[1,0] op_sel_hi:[0,0]
	s_waitcnt vmcnt(0)
; DEV unsigned pk_bf16(float lo, float hi) { unsigned r; asm("v_cvt_pk_bf16_f32 %0, %1, %2" : "=v"(r) : "v"(lo), "v"(hi)); return r; }
; DEV float2 cmulf(float2 a, float2 b) { return make_float2(a.x * b.x - a.y * b.y, a.x * b.y + a.y * b.x); }
; DEV void ef_item(const P& p, int l, int it) {
;     ...
; #pragma unroll
;   for (int c2 = 0; c2 < 8; ++c2) {
;     const size_t bi = ((size_t)gi * 64 + pp) * 16 + c2 * 2;
;     const float2 v0 = cmulf(wf, cmulf(f, make_float2(p.b_re[bi], p.b_im[bi])));
;     const float2 v1 = cmulf(wf, cmulf(f, make_float2(p.b_re[bi + 1], p.b_im[bi + 1])));
;     fr[c2] = pk_bf16(v0.x, v1.x); fi[c2] = pk_bf16(v0.y, v1.y);
;   }
	v_pk_fma_f32 v[2:3], v[28:29], v[10:11], v[0:1] op_sel_hi:[1,0,1]
	v_pk_fma_f32 v[0:1], v[28:29], v[10:11], v[0:1] op_sel_hi:[1,0,1] neg_lo:[0,0,1] neg_hi:[0,0,1]
	v_mov_b32_e32 v4, v2
	v_mov_b32_e32 v5, v1
	v_pk_mov_b32 v[0:1], v[0:1], v[2:3] op_sel:[1,0]
	s_nop 0
	v_pk_mul_f32 v[0:1], v[30:31], v[0:1]
	s_nop 0
	v_sub_f32_e32 v6, v0, v1
	v_pk_mul_f32 v[0:1], v[30:31], v[4:5]
	s_nop 0
	v_add_f32_e32 v7, v0, v1
	v_pk_mul_f32 v[0:1], v[28:29], v[20:21] op_sel:[1,1] op_sel_hi:[0,1]
	v_pk_fma_f32 v[2:3], v[28:29], v[10:11], v[0:1] op_sel:[0,1,0]
	v_pk_fma_f32 v[0:1], v[28:29], v[10:11], v[0:1] op_sel:[0,1,0] neg_lo:[0,0,1] neg_hi:[0,0,1]
	v_mov_b32_e32 v4, v2
	v_mov_b32_e32 v5, v1
	v_pk_mov_b32 v[0:1], v[0:1], v[2:3] op_sel:[1,0]
	s_nop 0
	v_pk_mul_f32 v[0:1], v[30:31], v[0:1]
	s_nop 0
	v_sub_f32_e32 v2, v0, v1
	v_pk_mul_f32 v[0:1], v[30:31], v[4:5]
	v_cvt_pk_bf16_f32 v4, v6, v2
	v_pk_mul_f32 v[2:3], v[28:29], v[22:23] op_sel:[1,0] op_sel_hi:[0,0]
	v_add_f32_e32 v0, v0, v1
	v_cvt_pk_bf16_f32 v0, v7, v0
	v_pk_fma_f32 v[6:7], v[28:29], v[12:13], v[2:3] op_sel_hi:[1,0,1]
	v_pk_fma_f32 v[2:3], v[28:29], v[12:13], v[2:3] op_sel_hi:[1,0,1] neg_lo:[0,0,1] neg_hi:[0,0,1]
	v_mov_b32_e32 v8, v6
	v_mov_b32_e32 v9, v3
	v_pk_mov_b32 v[2:3], v[2:3], v[6:7] op_sel:[1,0]
	s_nop 0
	v_pk_mul_f32 v[2:3], v[30:31], v[2:3]
	s_nop 0
	v_sub_f32_e32 v1, v2, v3
	v_pk_mul_f32 v[2:3], v[30:31], v[8:9]
	s_nop 0
	v_add_f32_e32 v10, v2, v3
	v_pk_mul_f32 v[2:3], v[28:29], v[22:23] op_sel:[1,1] op_sel_hi:[0,1]
	v_pk_fma_f32 v[6:7], v[28:29], v[12:13], v[2:3] op_sel:[0,1,0]
	v_pk_fma_f32 v[2:3], v[28:29], v[12:13], v[2:3] op_sel:[0,1,0] neg_lo:[0,0,1] neg_hi:[0,0,1]
	v_mov_b32_e32 v8, v6
	v_mov_b32_e32 v9, v3
	v_pk_mov_b32 v[2:3], v[2:3], v[6:7] op_sel:[1,0]
	s_nop 0
	v_pk_mul_f32 v[2:3], v[30:31], v[2:3]
	s_nop 0
	v_sub_f32_e32 v5, v2, v3
	v_pk_mul_f32 v[2:3], v[30:31], v[8:9]
	v_cvt_pk_bf16_f32 v5, v1, v5
	s_nop 0
	v_add_f32_e32 v2, v2, v3
	v_cvt_pk_bf16_f32 v1, v10, v2
	global_load_dwordx4 v[6:9], v[24:25], off offset:16
	global_load_dwordx4 v[10:13], v[26:27], off offset:16
	s_waitcnt vmcnt(0)
	v_pk_mul_f32 v[2:3], v[28:29], v[10:11] op_sel:[1,0] op_sel_hi:[0,0]
	v_pk_fma_f32 v[14:15], v[28:29], v[6:7], v[2:3] op_sel_hi:[1,0,1]
	v_pk_fma_f32 v[2:3], v[28:29], v[6:7], v[2:3] op_sel_hi:[1,0,1] neg_lo:[0,0,1] neg_hi:[0,0,1]
	v_mov_b32_e32 v20, v14
	v_mov_b32_e32 v21, v3
	v_pk_mov_b32 v[2:3], v[2:3], v[14:15] op_sel:[1,0]
	s_nop 0
	v_pk_mul_f32 v[2:3], v[30:31], v[2:3]
	s_nop 0
	v_sub_f32_e32 v14, v2, v3
	v_pk_mul_f32 v[2:3], v[30:31], v[20:21]
	s_nop 0
	v_add_f32_e32 v15, v2, v3
	v_pk_mul_f32 v[2:3], v[28:29], v[10:11] op_sel:[1,1] op_sel_hi:[0,1]
	v_pk_fma_f32 v[10:11], v[28:29], v[6:7], v[2:3] op_sel:[0,1,0]
	v_pk_fma_f32 v[2:3], v[28:29], v[6:7], v[2:3] op_sel:[0,1,0] neg_lo:[0,0,1] neg_hi:[0,0,1]
	v_mov_b32_e32 v6, v10
	v_mov_b32_e32 v7, v3
	v_pk_mov_b32 v[2:3], v[2:3], v[10:11] op_sel:[1,0]
	s_nop 0
	v_pk_mul_f32 v[2:3], v[30:31], v[2:3]
	s_nop 0
	v_sub_f32_e32 v10, v2, v3
	v_pk_mul_f32 v[2:3], v[30:31], v[6:7]
	v_cvt_pk_bf16_f32 v6, v14, v10
	v_pk_mul_f32 v[10:11], v[28:29], v[12:13] op_sel:[1,0] op_sel_hi:[0,0]
	v_add_f32_e32 v2, v2, v3
	v_cvt_pk_bf16_f32 v2, v15, v2
	v_pk_fma_f32 v[14:15], v[28:29], v[8:9], v[10:11] op_sel_hi:[1,0,1]
	v_pk_fma_f32 v[10:11], v[28:29], v[8:9], v[10:11] op_sel_hi:[1,0,1] neg_lo:[0,0,1] neg_hi:[0,0,1]
	v_mov_b32_e32 v20, v14
	v_mov_b32_e32 v21, v11
	v_pk_mov_b32 v[10:11], v[10:11], v[14:15] op_sel:[1,0]
	s_nop 0
	v_pk_mul_f32 v[10:11], v[30:31], v[10:11]
	s_nop 0
	v_sub_f32_e32 v3, v10, v11
	v_pk_mul_f32 v[10:11], v[30:31], v[20:21]
	s_nop 0
	v_add_f32_e32 v14, v10, v11
	v_pk_mul_f32 v[10:11], v[28:29], v[12:13] op_sel:[1,1] op_sel_hi:[0,1]
	v_pk_fma_f32 v[12:13], v[28:29], v[8:9], v[10:11] op_sel:[0,1,0]
	v_pk_fma_f32 v[8:9], v[28:29], v[8:9], v[10:11] op_sel:[0,1,0] neg_lo:[0,0,1] neg_hi:[0,0,1]
	v_mov_b32_e32 v10, v12
	v_mov_b32_e32 v11, v9
	v_pk_mov_b32 v[8:9], v[8:9], v[12:13] op_sel:[1,0]
	s_nop 0
	v_pk_mul_f32 v[8:9], v[30:31], v[8:9]
	s_nop 0
	v_sub_f32_e32 v7, v8, v9
	v_pk_mul_f32 v[8:9], v[30:31], v[10:11]
	v_cvt_pk_bf16_f32 v7, v3, v7
	s_nop 0
	v_add_f32_e32 v8, v8, v9
	v_cvt_pk_bf16_f32 v3, v14, v8
	global_load_dwordx4 v[8:11], v[24:25], off offset:32
	global_load_dwordx4 v[12:15], v[26:27], off offset:32
	s_waitcnt vmcnt(0)
; DEV unsigned pk_bf16(float lo, float hi) { unsigned r; asm("v_cvt_pk_bf16_f32 %0, %1, %2" : "=v"(r) : "v"(lo), "v"(hi)); return r; }
; DEV float2 cmulf(float2 a, float2 b) { return make_float2(a.x * b.x - a.y * b.y, a.x * b.y + a.y * b.x); }
; DEV void ef_item(const P& p, int l, int it) {
;     ...
; #pragma unroll
;   for (int c2 = 0; c2 < 8; ++c2) {
;     const size_t bi = ((size_t)gi * 64 + pp) * 16 + c2 * 2;
;     const float2 v0 = cmulf(wf, cmulf(f, make_float2(p.b_re[bi], p.b_im[bi])));
;     const float2 v1 = cmulf(wf, cmulf(f, make_float2(p.b_re[bi + 1], p.b_im[bi + 1])));
;     fr[c2] = pk_bf16(v0.x, v1.x); fi[c2] = pk_bf16(v0.y, v1.y);
;   }
;   u32x4* r0 = (u32x4*)(Ft + (size_t)(dir * 128 + pp * 2) * 512 + t * 16);
;   u32x4* r1 = (u32x4*)(Ft + (size_t)(dir * 128 + pp * 2 + 1) * 512 + t * 16);
;   r0[0] = (u32x4){fr[0], fr[1], fr[2], fr[3]}; r0[1] = (u32x4){fr[4], fr[5], fr[6], fr[7]};
;   r1[0] = (u32x4){fi[0], fi[1], fi[2], fi[3]}; r1[1] = (u32x4){fi[4], fi[5], fi[6], fi[7]};
	v_pk_mul_f32 v[20:21], v[28:29], v[12:13] op_sel:[1,0] op_sel_hi:[0,0]
	v_pk_fma_f32 v[22:23], v[28:29], v[8:9], v[20:21] op_sel_hi:[1,0,1]
	v_pk_fma_f32 v[20:21], v[28:29], v[8:9], v[20:21] op_sel_hi:[1,0,1] neg_lo:[0,0,1] neg_hi:[0,0,1]
	v_mov_b32_e32 v32, v22
	v_mov_b32_e32 v33, v21
	v_pk_mov_b32 v[20:21], v[20:21], v[22:23] op_sel:[1,0]
	v_pk_mul_f32 v[12:13], v[28:29], v[12:13] op_sel:[1,1] op_sel_hi:[0,1]
	v_pk_mul_f32 v[20:21], v[30:31], v[20:21]
	s_nop 0
	v_sub_f32_e32 v19, v20, v21
	v_pk_mul_f32 v[20:21], v[30:31], v[32:33]
	s_nop 0
	v_add_f32_e32 v22, v20, v21
	v_pk_fma_f32 v[20:21], v[28:29], v[8:9], v[12:13] op_sel:[0,1,0]
	v_pk_fma_f32 v[8:9], v[28:29], v[8:9], v[12:13] op_sel:[0,1,0] neg_lo:[0,0,1] neg_hi:[0,0,1]
	v_mov_b32_e32 v12, v20
	v_mov_b32_e32 v13, v9
	v_pk_mov_b32 v[8:9], v[8:9], v[20:21] op_sel:[1,0]
	s_nop 0
	v_pk_mul_f32 v[8:9], v[30:31], v[8:9]
	s_nop 0
	v_sub_f32_e32 v20, v8, v9
	v_pk_mul_f32 v[8:9], v[30:31], v[12:13]
	v_cvt_pk_bf16_f32 v12, v19, v20
	v_pk_mul_f32 v[20:21], v[28:29], v[14:15] op_sel:[1,0] op_sel_hi:[0,0]
	v_add_f32_e32 v8, v8, v9
	v_cvt_pk_bf16_f32 v8, v22, v8
	v_pk_fma_f32 v[22:23], v[28:29], v[10:11], v[20:21] op_sel_hi:[1,0,1]
	v_pk_fma_f32 v[20:21], v[28:29], v[10:11], v[20:21] op_sel_hi:[1,0,1] neg_lo:[0,0,1] neg_hi:[0,0,1]
	v_mov_b32_e32 v32, v22
	v_mov_b32_e32 v33, v21
	v_pk_mov_b32 v[20:21], v[20:21], v[22:23] op_sel:[1,0]
	v_pk_mul_f32 v[14:15], v[28:29], v[14:15] op_sel:[1,1] op_sel_hi:[0,1]
	v_pk_mul_f32 v[20:21], v[30:31], v[20:21]
	s_nop 0
	v_sub_f32_e32 v9, v20, v21
	v_pk_mul_f32 v[20:21], v[30:31], v[32:33]
	s_nop 0
	v_add_f32_e32 v19, v20, v21
	v_pk_fma_f32 v[20:21], v[28:29], v[10:11], v[14:15] op_sel:[0,1,0]
	v_pk_fma_f32 v[10:11], v[28:29], v[10:11], v[14:15] op_sel:[0,1,0] neg_lo:[0,0,1] neg_hi:[0,0,1]
	v_mov_b32_e32 v14, v20
	v_mov_b32_e32 v15, v11
	v_pk_mov_b32 v[10:11], v[10:11], v[20:21] op_sel:[1,0]
	global_load_dwordx4 v[20:23], v[24:25], off offset:48
	s_nop 0
	global_load_dwordx4 v[24:27], v[26:27], off offset:48
	v_pk_mul_f32 v[10:11], v[30:31], v[10:11]
	s_nop 0
	v_sub_f32_e32 v13, v10, v11
	v_pk_mul_f32 v[10:11], v[30:31], v[14:15]
	v_cvt_pk_bf16_f32 v13, v9, v13
	s_nop 0
	v_add_f32_e32 v10, v10, v11
	v_cvt_pk_bf16_f32 v9, v19, v10
	s_waitcnt vmcnt(0)
	v_pk_mul_f32 v[10:11], v[28:29], v[24:25] op_sel:[1,0] op_sel_hi:[0,0]
	v_pk_fma_f32 v[14:15], v[28:29], v[20:21], v[10:11] op_sel_hi:[1,0,1]
	v_pk_fma_f32 v[10:11], v[28:29], v[20:21], v[10:11] op_sel_hi:[1,0,1] neg_lo:[0,0,1] neg_hi:[0,0,1]
	v_mov_b32_e32 v32, v14
	v_mov_b32_e32 v33, v11
	v_pk_mov_b32 v[10:11], v[10:11], v[14:15] op_sel:[1,0]
	s_nop 0
	v_pk_mul_f32 v[10:11], v[30:31], v[10:11]
	s_nop 0
	v_sub_f32_e32 v19, v10, v11
	v_pk_mul_f32 v[10:11], v[30:31], v[32:33]
	s_nop 0
	v_add_f32_e32 v32, v10, v11
	v_pk_mul_f32 v[10:11], v[28:29], v[24:25] op_sel:[1,1] op_sel_hi:[0,1]
	v_pk_fma_f32 v[14:15], v[28:29], v[20:21], v[10:11] op_sel:[0,1,0]
	v_pk_fma_f32 v[10:11], v[28:29], v[20:21], v[10:11] op_sel:[0,1,0] neg_lo:[0,0,1] neg_hi:[0,0,1]
	v_mov_b32_e32 v20, v14
	v_mov_b32_e32 v21, v11
	v_pk_mov_b32 v[10:11], v[10:11], v[14:15] op_sel:[1,0]
	s_nop 0
	v_pk_mul_f32 v[10:11], v[30:31], v[10:11]
	s_nop 0
	v_sub_f32_e32 v14, v10, v11
	v_pk_mul_f32 v[10:11], v[30:31], v[20:21]
	v_pk_mul_f32 v[20:21], v[28:29], v[26:27] op_sel:[1,0] op_sel_hi:[0,0]
	v_pk_fma_f32 v[24:25], v[28:29], v[22:23], v[20:21] op_sel_hi:[1,0,1]
	v_pk_fma_f32 v[20:21], v[28:29], v[22:23], v[20:21] op_sel_hi:[1,0,1] neg_lo:[0,0,1] neg_hi:[0,0,1]
	v_add_f32_e32 v10, v10, v11
	v_mov_b32_e32 v33, v21
	v_pk_mov_b32 v[20:21], v[20:21], v[24:25] op_sel:[1,0]
	v_cvt_pk_bf16_f32 v10, v32, v10
	v_mov_b32_e32 v32, v24
	v_pk_mul_f32 v[20:21], v[30:31], v[20:21]
	v_cvt_pk_bf16_f32 v14, v19, v14
	s_nop 0
	v_sub_f32_e32 v11, v20, v21
	v_pk_mul_f32 v[20:21], v[30:31], v[32:33]
	s_nop 0
	v_add_f32_e32 v19, v20, v21
	v_pk_mul_f32 v[20:21], v[28:29], v[26:27] op_sel:[1,1] op_sel_hi:[0,1]
	v_pk_fma_f32 v[24:25], v[28:29], v[22:23], v[20:21] op_sel:[0,1,0]
	v_pk_fma_f32 v[20:21], v[28:29], v[22:23], v[20:21] op_sel:[0,1,0] neg_lo:[0,0,1] neg_hi:[0,0,1]
	v_mov_b32_e32 v22, v24
	v_mov_b32_e32 v23, v21
	v_pk_mov_b32 v[20:21], v[20:21], v[24:25] op_sel:[1,0]
	s_nop 0
	v_pk_mul_f32 v[20:21], v[30:31], v[20:21]
	s_nop 0
	v_sub_f32_e32 v15, v20, v21
	v_pk_mul_f32 v[20:21], v[30:31], v[22:23]
	v_cvt_pk_bf16_f32 v15, v11, v15
	s_nop 0
	v_add_f32_e32 v20, v20, v21
	v_cvt_pk_bf16_f32 v11, v19, v20
	v_ashrrev_i32_e32 v19, 31, v18
	v_lshlrev_b64 v[20:21], 10, v[18:19]
	v_or_b32_e32 v18, 1, v18
	v_ashrrev_i32_e32 v19, 31, v18
	v_lshl_add_u64 v[20:21], s[4:5], 0, v[20:21]
	v_lshlrev_b64 v[18:19], 10, v[18:19]
	v_lshl_add_u64 v[16:17], v[20:21], 0, v[40:41]
	v_lshl_add_u64 v[18:19], s[4:5], 0, v[18:19]
	v_lshl_add_u64 v[18:19], v[18:19], 0, v[40:41]
	global_store_dwordx4 v[16:17], v[4:7], off
	global_store_dwordx4 v[16:17], v[12:15], off offset:16
	global_store_dwordx4 v[18:19], v[0:3], off
	global_store_dwordx4 v[18:19], v[8:11], off offset:16
	s_cbranch_scc1 .LBB0_96
	v_readlane_b32 s51, v254, 38

; DEV int get_tid() { int t; asm volatile("v_mov_b32 %0, %1" : "=v"(t) : "v"((int)(threadIdx.x & 255))); return t; }
; DEV unsigned pk_bf16(float lo, float hi) { unsigned r; asm("v_cvt_pk_bf16_f32 %0, %1, %2" : "=v"(r) : "v"(lo), "v"(hi)); return r; }
; DEV float2 cmulf(float2 a, float2 b) { return make_float2(a.x * b.x - a.y * b.y, a.x * b.y + a.y * b.x); }
; DEV Disc s5_disc(const P& p, int l, int dir, int g, int pp) {
;   Disc d; const int gi = (l * 2 + dir) * 32 + g;
;   d.dt = (double)expf(p.log_dt[gi]); d.are = p.a_re[gi * 64 + pp]; d.aim = p.a_im[gi * 64 + pp];
;   const float mag = __expf((float)(d.dt * (double)d.are)); float sn, cs; sincos_d(d.dt * (double)d.aim, sn, cs);
;   const float abr = mag * cs, abi = mag * sn, den = d.are * d.are + d.aim * d.aim, nr = abr - 1.0f, ni = abi;
;   d.fre = (nr * d.are + ni * d.aim) / den; d.fim = (ni * d.are - nr * d.aim) / den;
;   return d;
; }
; DEV float2 cpow(const Disc& d, int e) {
;   const float mag = __expf((float)((double)e * d.dt * (double)d.are)); float sn, cs; sincos_d((double)e * d.dt * (double)d.aim, sn, cs);
;   return make_float2(mag * cs, mag * sn);
; }
; DEV void ef_item(const P& p, int l, int it) {
;   const int g = it >> 4, id = (it & 15) * 256 + get_tid();
;   const int t = id & 31, pp = (id >> 5) & 63, dir = id >> 11, gi = (l * 2 + dir) * 32 + g;
;   const Disc d = s5_disc(p, l, dir, g, pp);
;   const float2 we = cpow(d, dir == 0 ? t + 1 : 32 - t), wf = cpow(d, dir == 0 ? 31 - t : t);
;   unsigned* Et = (unsigned*)(p.ws + OFF_ET) + (size_t)g * 512 * 128;
;   bf16_t* Ft = (bf16_t*)(p.ws + OFF_FT) + (size_t)g * 256 * 512;
; #pragma unroll
;   for (int c = 0; c < 16; ++c) {
;     const float2 cc = make_float2(p.c_re[((size_t)gi * 16 + c) * 64 + pp], p.c_im[((size_t)gi * 16 + c) * 64 + pp]);
;     const float2 cw = cmulf(cc, we);
;     Et[(size_t)(t * 16 + c) * 128 + dir * 64 + pp] = pk_bf16(cw.x, -cw.y);
;   }
.LBB0_442:
	s_and_b32 s7, s12, 0xf00
	v_mov_b32 v19, v238
	s_ashr_i32 s6, s2, 4
	v_add_u32_e32 v12, s7, v19
	v_ashrrev_i32_e32 v18, 11, v12
	v_lshl_add_u32 v4, v18, 5, s6
	v_ashrrev_i32_e32 v5, 31, v4
	v_lshl_add_u64 v[0:1], v[4:5], 2, s[62:63]
	global_load_dword v0, v[0:1], off
	v_bfe_u32 v17, v12, 5, 6
	v_and_b32_e32 v16, 31, v19
	s_ashr_i32 s7, s6, 31
	s_lshl_b64 s[6:7], s[6:7], 18
	s_add_u32 s14, s3, s6
	s_addc_u32 s15, s8, s7
	v_lshlrev_b32_e32 v40, 2, v17
	s_add_u32 s6, s9, s6
	s_addc_u32 s7, s10, s7
	s_add_i32 s2, s2, s91
	s_add_i32 s12, s12, s19
	s_cmpk_lt_i32 s2, 0x200
	s_waitcnt vmcnt(0)
	v_mul_f32_e32 v1, 0x3fb8aa3b, v0
	v_fma_f32 v2, v0, s23, -v1
	v_rndne_f32_e32 v3, v1
	v_fmac_f32_e32 v2, 0x32a5705f, v0
	v_sub_f32_e32 v1, v1, v3
	v_add_f32_e32 v1, v1, v2
	v_exp_f32_e32 v1, v1
	v_cvt_i32_f32_e32 v2, v3
	v_cmp_ngt_f32_e32 vcc, s24, v0
	v_ldexp_f32 v1, v1, v2
	s_nop 0
	v_cndmask_b32_e32 v1, 0, v1, vcc
	v_cmp_nlt_f32_e32 vcc, s25, v0
	v_lshl_or_b32 v0, v4, 6, v17
	v_lshlrev_b64 v[4:5], 10, v[4:5]
	v_cndmask_b32_e32 v8, v236, v1, vcc
	v_ashrrev_i32_e32 v1, 31, v0
	v_lshlrev_b64 v[2:3], 2, v[0:1]
	v_lshl_add_u64 v[0:1], s[58:59], 0, v[2:3]
	global_load_dword v0, v[0:1], off
	v_lshl_add_u64 v[2:3], s[60:61], 0, v[2:3]
	global_load_dword v1, v[2:3], off
	v_cvt_f64_f32_e32 v[6:7], v8
	v_cmp_gt_u32_e32 vcc, s13, v12
	s_waitcnt vmcnt(1)
	v_mul_f32_e32 v2, v8, v0
	v_mul_f32_e32 v2, 0x3fb8aa3b, v2
	s_waitcnt vmcnt(0)
	v_cvt_f64_f32_e32 v[8:9], v1
	v_exp_f32_e32 v13, v2
	v_mul_f64 v[2:3], v[6:7], v[8:9]
	v_mul_f64 v[10:11], v[2:3], s[28:29]
	v_rndne_f64_e32 v[10:11], v[10:11]
	v_fmac_f64_e32 v[2:3], s[30:31], v[10:11]
	v_mul_f64 v[2:3], v[2:3], s[28:29]
	v_cvt_f32_f64_e32 v2, v[2:3]
	v_sin_f32_e32 v3, v2
	v_cos_f32_e32 v10, v2
	v_sub_u32_e32 v11, 32, v16
	v_mul_f32_e32 v2, v13, v3
	v_fma_f32 v3, v13, v10, -1.0
	v_add_u32_e32 v10, 1, v16
	v_cndmask_b32_e32 v10, v11, v10, vcc
	v_cvt_f64_u32_e32 v[10:11], v10
	v_mul_f64 v[12:13], v[6:7], v[10:11]
	v_cvt_f64_f32_e32 v[10:11], v0
	v_mul_f64 v[14:15], v[12:13], v[10:11]
	v_cvt_f32_f64_e32 v14, v[14:15]
	v_mul_f32_e32 v14, 0x3fb8aa3b, v14
	v_mul_f64 v[12:13], v[12:13], v[8:9]
	v_exp_f32_e32 v20, v14
	v_mul_f64 v[14:15], v[12:13], s[28:29]
	v_rndne_f64_e32 v[14:15], v[14:15]
	v_fmac_f64_e32 v[12:13], s[30:31], v[14:15]
	v_bitop3_b32 v14, v19, 31, v19 bitop3:0xc
	v_cndmask_b32_e32 v14, v16, v14, vcc
	v_cvt_f64_u32_e32 v[14:15], v14
	v_mul_f64 v[12:13], v[12:13], s[28:29]
	v_mul_f64 v[14:15], v[6:7], v[14:15]
	v_cvt_f32_f64_e32 v12, v[12:13]
	v_mul_f64 v[8:9], v[14:15], v[8:9]
	v_sin_f32_e32 v13, v12
	v_cos_f32_e32 v12, v12
	v_mul_f64 v[6:7], v[14:15], v[10:11]
	v_mul_f64 v[10:11], v[8:9], s[28:29]
	v_rndne_f64_e32 v[10:11], v[10:11]
	v_fmac_f64_e32 v[8:9], s[30:31], v[10:11]
	v_or_b32_e32 v10, v4, v17
	v_mov_b32_e32 v11, v5
	v_lshlrev_b64 v[10:11], 2, v[10:11]
	v_mul_f32_e32 v12, v20, v12
	v_mul_f32_e32 v13, v20, v13
	v_lshl_add_u64 v[20:21], s[68:69], 0, v[10:11]
	v_lshl_add_u64 v[10:11], s[70:71], 0, v[10:11]
	v_mul_f64 v[8:9], v[8:9], s[28:29]
	global_load_dword v19, v[10:11], off
	v_cvt_f32_f64_e32 v6, v[6:7]
	v_cvt_f32_f64_e32 v7, v[8:9]
	global_load_dword v9, v[20:21], off
	v_lshlrev_b32_e32 v14, 6, v18
	v_ashrrev_i32_e32 v15, 31, v14
	v_lshl_add_u64 v[14:15], v[14:15], 2, s[14:15]
	v_lshl_add_u64 v[14:15], v[14:15], 0, v[40:41]
	v_lshlrev_b32_e32 v40, 13, v16
	v_lshl_add_u64 v[14:15], v[14:15], 0, v[40:41]
	v_lshl_or_b32 v4, v17, 4, v4
	v_lshlrev_b64 v[4:5], 2, v[4:5]
	v_lshl_add_u64 v[26:27], s[66:67], 0, v[4:5]
	v_lshl_add_u64 v[24:25], s[64:65], 0, v[4:5]
	v_mov_b32_e32 v4, v1
	v_pk_mul_f32 v[4:5], v[4:5], v[2:3] op_sel:[0,1] op_sel_hi:[0,0]
	v_pk_fma_f32 v[28:29], v[0:1], v[2:3], v[4:5] neg_lo:[0,0,1] neg_hi:[0,0,1]
	v_cos_f32_e32 v8, v7
	v_mul_f32_e32 v6, 0x3fb8aa3b, v6
	v_exp_f32_e32 v6, v6
	v_lshlrev_b32_e32 v18, 7, v18
	v_lshl_or_b32 v18, v17, 1, v18
	v_lshlrev_b32_e32 v40, 5, v16
	s_waitcnt vmcnt(1)
	v_mul_f32_e32 v22, v19, v13
	v_mul_f32_e32 v19, v19, v12
	s_waitcnt vmcnt(0)
	v_fmac_f32_e32 v19, v9, v13
	v_fma_f32 v22, v9, v12, -v22
	v_xor_b32_e32 v9, 0x80000000, v19
	v_cvt_pk_bf16_f32 v9, v22, v9
	global_store_dword v[14:15], v9, off
	global_load_dword v102, v[20:21], off offset:256
	global_load_dword v103, v[10:11], off offset:256
	global_load_dword v104, v[20:21], off offset:512
	global_load_dword v105, v[10:11], off offset:512
	global_load_dword v106, v[20:21], off offset:768
	global_load_dword v107, v[10:11], off offset:768
	global_load_dword v108, v[20:21], off offset:1024
	global_load_dword v109, v[10:11], off offset:1024
	global_load_dword v110, v[20:21], off offset:1280
	global_load_dword v111, v[10:11], off offset:1280
	global_load_dword v112, v[20:21], off offset:1536
	global_load_dword v113, v[10:11], off offset:1536
	global_load_dword v114, v[20:21], off offset:1792
	global_load_dword v115, v[10:11], off offset:1792
	global_load_dword v116, v[20:21], off offset:2048
	global_load_dword v117, v[10:11], off offset:2048
	global_load_dword v118, v[20:21], off offset:2304
	global_load_dword v119, v[10:11], off offset:2304
	global_load_dword v120, v[20:21], off offset:2560
	global_load_dword v121, v[10:11], off offset:2560
	global_load_dword v122, v[20:21], off offset:2816
	global_load_dword v123, v[10:11], off offset:2816
	global_load_dword v124, v[20:21], off offset:3072
	global_load_dword v125, v[10:11], off offset:3072
	global_load_dword v126, v[20:21], off offset:3328
	global_load_dword v127, v[10:11], off offset:3328
	global_load_dword v128, v[20:21], off offset:3584
	global_load_dword v129, v[10:11], off offset:3584
	global_load_dword v130, v[20:21], off offset:3840
	global_load_dword v131, v[10:11], off offset:3840
	s_waitcnt vmcnt(28)
; DEV unsigned pk_bf16(float lo, float hi) { unsigned r; asm("v_cvt_pk_bf16_f32 %0, %1, %2" : "=v"(r) : "v"(lo), "v"(hi)); return r; }
; DEV float2 cmulf(float2 a, float2 b) { return make_float2(a.x * b.x - a.y * b.y, a.x * b.y + a.y * b.x); }
; DEV Disc s5_disc(const P& p, int l, int dir, int g, int pp) {
;     ...
;   const float abr = mag * cs, abi = mag * sn, den = d.are * d.are + d.aim * d.aim, nr = abr - 1.0f, ni = abi;
;   d.fre = (nr * d.are + ni * d.aim) / den; d.fim = (ni * d.are - nr * d.aim) / den;
; DEV void ef_item(const P& p, int l, int it) {
;     ...
;   for (int c = 0; c < 16; ++c) {
;     const float2 cc = make_float2(p.c_re[((size_t)gi * 16 + c) * 64 + pp], p.c_im[((size_t)gi * 16 + c) * 64 + pp]);
;     const float2 cw = cmulf(cc, we);
;     Et[(size_t)(t * 16 + c) * 128 + dir * 64 + pp] = pk_bf16(cw.x, -cw.y);
;   }
;   const float2 f = make_float2(d.fre, d.fim);
;   unsigned fr[8], fi[8];
; #pragma unroll
;   for (int c2 = 0; c2 < 8; ++c2) {
;     const size_t bi = ((size_t)gi * 64 + pp) * 16 + c2 * 2;
;     const float2 v0 = cmulf(wf, cmulf(f, make_float2(p.b_re[bi], p.b_im[bi])));
;     const float2 v1 = cmulf(wf, cmulf(f, make_float2(p.b_re[bi + 1], p.b_im[bi + 1])));
;     fr[c2] = pk_bf16(v0.x, v1.x); fi[c2] = pk_bf16(v0.y, v1.y);
	v_mul_f32_e32 v22, v103, v13
	v_mul_f32_e32 v19, v103, v12
	v_fmac_f32_e32 v19, v102, v13
	v_fma_f32 v22, v102, v12, -v22
	v_xor_b32_e32 v9, 0x80000000, v19
	v_cvt_pk_bf16_f32 v9, v22, v9
	global_store_dword v[14:15], v9, off offset:512
	s_waitcnt vmcnt(27)
	v_mul_f32_e32 v22, v105, v13
	v_mul_f32_e32 v19, v105, v12
	v_fmac_f32_e32 v19, v104, v13
	v_fma_f32 v22, v104, v12, -v22
	v_xor_b32_e32 v9, 0x80000000, v19
	v_cvt_pk_bf16_f32 v9, v22, v9
	global_store_dword v[14:15], v9, off offset:1024
	s_waitcnt vmcnt(26)
	v_mul_f32_e32 v22, v13, v107
	v_mul_f32_e32 v19, v12, v107
	v_fmac_f32_e32 v19, v13, v106
	v_fma_f32 v22, v12, v106, -v22
	v_xor_b32_e32 v9, 0x80000000, v19
	v_cvt_pk_bf16_f32 v9, v22, v9
	global_store_dword v[14:15], v9, off offset:1536
	s_waitcnt vmcnt(25)
	v_mul_f32_e32 v22, v13, v109
	v_mul_f32_e32 v19, v12, v109
	v_fmac_f32_e32 v19, v13, v108
	v_fma_f32 v22, v12, v108, -v22
	v_xor_b32_e32 v9, 0x80000000, v19
	v_cvt_pk_bf16_f32 v9, v22, v9
	global_store_dword v[14:15], v9, off offset:2048
	s_waitcnt vmcnt(24)
	v_mul_f32_e32 v22, v13, v111
	v_mul_f32_e32 v19, v12, v111
	v_fmac_f32_e32 v19, v13, v110
	v_fma_f32 v22, v12, v110, -v22
	v_xor_b32_e32 v9, 0x80000000, v19
	v_cvt_pk_bf16_f32 v9, v22, v9
	global_store_dword v[14:15], v9, off offset:2560
	s_waitcnt vmcnt(23)
	v_mul_f32_e32 v22, v13, v113
	v_mul_f32_e32 v19, v12, v113
	v_fmac_f32_e32 v19, v13, v112
	v_fma_f32 v22, v12, v112, -v22
	v_xor_b32_e32 v9, 0x80000000, v19
	v_cvt_pk_bf16_f32 v9, v22, v9
	global_store_dword v[14:15], v9, off offset:3072
	s_waitcnt vmcnt(22)
	v_mul_f32_e32 v22, v13, v115
	v_mul_f32_e32 v19, v12, v115
	v_fmac_f32_e32 v19, v13, v114
	v_fma_f32 v22, v12, v114, -v22
	v_xor_b32_e32 v9, 0x80000000, v19
	v_cvt_pk_bf16_f32 v9, v22, v9
	global_store_dword v[14:15], v9, off offset:3584
	v_add_co_u32_e32 v14, vcc, s11, v14
	s_waitcnt vmcnt(21)
	v_mul_f32_e32 v22, v13, v117
	v_mul_f32_e32 v19, v12, v117
	v_fmac_f32_e32 v19, v13, v116
	v_fma_f32 v22, v12, v116, -v22
	v_xor_b32_e32 v9, 0x80000000, v19
	v_addc_co_u32_e32 v15, vcc, 0, v15, vcc
	v_cvt_pk_bf16_f32 v9, v22, v9
	global_store_dword v[14:15], v9, off
	s_waitcnt vmcnt(20)
	v_mul_f32_e32 v22, v13, v119
	v_mul_f32_e32 v19, v12, v119
	v_fmac_f32_e32 v19, v13, v118
	v_fma_f32 v22, v12, v118, -v22
	v_xor_b32_e32 v9, 0x80000000, v19
	v_cvt_pk_bf16_f32 v9, v22, v9
	global_store_dword v[14:15], v9, off offset:512
	s_waitcnt vmcnt(19)
	v_mul_f32_e32 v22, v13, v121
	v_mul_f32_e32 v19, v12, v121
	v_fmac_f32_e32 v19, v13, v120
	v_fma_f32 v22, v12, v120, -v22
	v_xor_b32_e32 v9, 0x80000000, v19
	v_cvt_pk_bf16_f32 v9, v22, v9
	global_store_dword v[14:15], v9, off offset:1024
	s_waitcnt vmcnt(18)
	v_mul_f32_e32 v22, v13, v123
	v_mul_f32_e32 v19, v12, v123
	v_fmac_f32_e32 v19, v13, v122
	v_fma_f32 v22, v12, v122, -v22
	v_xor_b32_e32 v9, 0x80000000, v19
	v_cvt_pk_bf16_f32 v9, v22, v9
	global_store_dword v[14:15], v9, off offset:1536
	s_waitcnt vmcnt(17)
	v_mul_f32_e32 v22, v13, v125
	v_mul_f32_e32 v19, v12, v125
	v_fmac_f32_e32 v19, v13, v124
	v_fma_f32 v22, v12, v124, -v22
	v_xor_b32_e32 v9, 0x80000000, v19
	v_cvt_pk_bf16_f32 v9, v22, v9
	global_store_dword v[14:15], v9, off offset:2048
	s_waitcnt vmcnt(16)
	v_mul_f32_e32 v22, v13, v127
	v_mul_f32_e32 v19, v12, v127
	v_fmac_f32_e32 v19, v13, v126
	v_fma_f32 v22, v12, v126, -v22
	v_xor_b32_e32 v9, 0x80000000, v19
	v_cvt_pk_bf16_f32 v9, v22, v9
	global_store_dword v[14:15], v9, off offset:2560
	s_waitcnt vmcnt(15)
	v_mul_f32_e32 v22, v13, v129
	v_mul_f32_e32 v19, v12, v129
	v_fmac_f32_e32 v19, v13, v128
	v_fma_f32 v22, v12, v128, -v22
	v_xor_b32_e32 v9, 0x80000000, v19
	v_cvt_pk_bf16_f32 v9, v22, v9
	global_store_dword v[14:15], v9, off offset:3072
	s_waitcnt vmcnt(14)
	v_mul_f32_e32 v11, v13, v131
	v_mul_f32_e32 v10, v12, v131
	v_fmac_f32_e32 v10, v13, v130
	v_fma_f32 v11, v12, v130, -v11
	v_xor_b32_e32 v9, 0x80000000, v10
	v_cvt_pk_bf16_f32 v9, v11, v9
	global_store_dword v[14:15], v9, off offset:3584
	global_load_dwordx4 v[20:23], v[26:27], off
	global_load_dwordx4 v[10:13], v[24:25], off
	v_pk_mul_f32 v[14:15], v[0:1], v[0:1]
	v_pk_fma_f32 v[0:1], v[0:1], v[2:3], v[4:5] op_sel_hi:[0,1,1]
	v_pk_add_f32 v[2:3], v[14:15], v[14:15] op_sel:[0,1] op_sel_hi:[0,1]
	v_div_scale_f32 v0, s[14:15], v3, v3, v1
	v_rcp_f32_e32 v4, v0
	v_sin_f32_e32 v9, v7
	v_fma_f32 v5, -v0, v4, 1.0
	v_fmac_f32_e32 v4, v5, v4
	v_div_scale_f32 v5, vcc, v1, v3, v1
	v_mul_f32_e32 v7, v5, v4
	v_fma_f32 v14, -v0, v7, v5
	v_fmac_f32_e32 v7, v14, v4
	v_fma_f32 v0, -v0, v7, v5
	v_div_fmas_f32 v0, v0, v4, v7
	v_div_fixup_f32 v29, v0, v3, v1
	v_div_scale_f32 v0, s[14:15], v2, v2, v28
	v_rcp_f32_e32 v1, v0
	v_pk_mul_f32 v[30:31], v[6:7], v[8:9] op_sel_hi:[0,1]
	v_fma_f32 v3, -v0, v1, 1.0
	v_fmac_f32_e32 v1, v3, v1
	v_div_scale_f32 v3, vcc, v28, v2, v28
	v_mul_f32_e32 v4, v3, v1
	v_fma_f32 v5, -v0, v4, v3
	v_fmac_f32_e32 v4, v5, v1
	v_fma_f32 v0, -v0, v4, v3
	v_div_fmas_f32 v0, v0, v1, v4
	v_div_fixup_f32 v28, v0, v2, v28
	s_waitcnt vmcnt(1)
	v_pk_mul_f32 v[0:1], v[28:29], v[20:21] op_sel:[1,0] op_sel_hi:[0,0]
	s_waitcnt vmcnt(0)
; DEV unsigned pk_bf16(float lo, float hi) { unsigned r; asm("v_cvt_pk_bf16_f32 %0, %1, %2" : "=v"(r) : "v"(lo), "v"(hi)); return r; }
; DEV float2 cmulf(float2 a, float2 b) { return make_float2(a.x * b.x - a.y * b.y, a.x * b.y + a.y * b.x); }
; DEV void ef_item(const P& p, int l, int it) {
;     ...
; #pragma unroll
;   for (int c2 = 0; c2 < 8; ++c2) {
;     const size_t bi = ((size_t)gi * 64 + pp) * 16 + c2 * 2;
;     const float2 v0 = cmulf(wf, cmulf(f, make_float2(p.b_re[bi], p.b_im[bi])));
;     const float2 v1 = cmulf(wf, cmulf(f, make_float2(p.b_re[bi + 1], p.b_im[bi + 1])));
;     fr[c2] = pk_bf16(v0.x, v1.x); fi[c2] = pk_bf16(v0.y, v1.y);
;   }
	v_pk_fma_f32 v[2:3], v[28:29], v[10:11], v[0:1] op_sel_hi:[1,0,1]
	v_pk_fma_f32 v[0:1], v[28:29], v[10:11], v[0:1] op_sel_hi:[1,0,1] neg_lo:[0,0,1] neg_hi:[0,0,1]
	v_mov_b32_e32 v4, v2
	v_mov_b32_e32 v5, v1
	v_pk_mov_b32 v[0:1], v[0:1], v[2:3] op_sel:[1,0]
	s_nop 0
	v_pk_mul_f32 v[0:1], v[30:31], v[0:1]
	s_nop 0
	v_sub_f32_e32 v6, v0, v1
	v_pk_mul_f32 v[0:1], v[30:31], v[4:5]
	s_nop 0
	v_add_f32_e32 v7, v0, v1
	v_pk_mul_f32 v[0:1], v[28:29], v[20:21] op_sel:[1,1] op_sel_hi:[0,1]
	v_pk_fma_f32 v[2:3], v[28:29], v[10:11], v[0:1] op_sel:[0,1,0]
	v_pk_fma_f32 v[0:1], v[28:29], v[10:11], v[0:1] op_sel:[0,1,0] neg_lo:[0,0,1] neg_hi:[0,0,1]
	v_mov_b32_e32 v4, v2
	v_mov_b32_e32 v5, v1
	v_pk_mov_b32 v[0:1], v[0:1], v[2:3] op_sel:[1,0]
	s_nop 0
	v_pk_mul_f32 v[0:1], v[30:31], v[0:1]
	s_nop 0
	v_sub_f32_e32 v2, v0, v1
	v_pk_mul_f32 v[0:1], v[30:31], v[4:5]
	v_cvt_pk_bf16_f32 v4, v6, v2
	v_pk_mul_f32 v[2:3], v[28:29], v[22:23] op_sel:[1,0] op_sel_hi:[0,0]
	v_add_f32_e32 v0, v0, v1
	v_cvt_pk_bf16_f32 v0, v7, v0
	v_pk_fma_f32 v[6:7], v[28:29], v[12:13], v[2:3] op_sel_hi:[1,0,1]
	v_pk_fma_f32 v[2:3], v[28:29], v[12:13], v[2:3] op_sel_hi:[1,0,1] neg_lo:[0,0,1] neg_hi:[0,0,1]
	v_mov_b32_e32 v8, v6
	v_mov_b32_e32 v9, v3
	v_pk_mov_b32 v[2:3], v[2:3], v[6:7] op_sel:[1,0]
	s_nop 0
	v_pk_mul_f32 v[2:3], v[30:31], v[2:3]
	s_nop 0
	v_sub_f32_e32 v1, v2, v3
	v_pk_mul_f32 v[2:3], v[30:31], v[8:9]
	s_nop 0
	v_add_f32_e32 v10, v2, v3
	v_pk_mul_f32 v[2:3], v[28:29], v[22:23] op_sel:[1,1] op_sel_hi:[0,1]
	v_pk_fma_f32 v[6:7], v[28:29], v[12:13], v[2:3] op_sel:[0,1,0]
	v_pk_fma_f32 v[2:3], v[28:29], v[12:13], v[2:3] op_sel:[0,1,0] neg_lo:[0,0,1] neg_hi:[0,0,1]
	v_mov_b32_e32 v8, v6
	v_mov_b32_e32 v9, v3
	v_pk_mov_b32 v[2:3], v[2:3], v[6:7] op_sel:[1,0]
	s_nop 0
	v_pk_mul_f32 v[2:3], v[30:31], v[2:3]
	s_nop 0
	v_sub_f32_e32 v5, v2, v3
	v_pk_mul_f32 v[2:3], v[30:31], v[8:9]
	v_cvt_pk_bf16_f32 v5, v1, v5
	s_nop 0
	v_add_f32_e32 v2, v2, v3
	v_cvt_pk_bf16_f32 v1, v10, v2
	global_load_dwordx4 v[6:9], v[24:25], off offset:16
	global_load_dwordx4 v[10:13], v[26:27], off offset:16
	s_waitcnt vmcnt(0)
	v_pk_mul_f32 v[2:3], v[28:29], v[10:11] op_sel:[1,0] op_sel_hi:[0,0]
	v_pk_fma_f32 v[14:15], v[28:29], v[6:7], v[2:3] op_sel_hi:[1,0,1]
	v_pk_fma_f32 v[2:3], v[28:29], v[6:7], v[2:3] op_sel_hi:[1,0,1] neg_lo:[0,0,1] neg_hi:[0,0,1]
	v_mov_b32_e32 v20, v14
	v_mov_b32_e32 v21, v3
	v_pk_mov_b32 v[2:3], v[2:3], v[14:15] op_sel:[1,0]
	s_nop 0
	v_pk_mul_f32 v[2:3], v[30:31], v[2:3]
	s_nop 0
	v_sub_f32_e32 v14, v2, v3
	v_pk_mul_f32 v[2:3], v[30:31], v[20:21]
	s_nop 0
	v_add_f32_e32 v15, v2, v3
	v_pk_mul_f32 v[2:3], v[28:29], v[10:11] op_sel:[1,1] op_sel_hi:[0,1]
	v_pk_fma_f32 v[10:11], v[28:29], v[6:7], v[2:3] op_sel:[0,1,0]
	v_pk_fma_f32 v[2:3], v[28:29], v[6:7], v[2:3] op_sel:[0,1,0] neg_lo:[0,0,1] neg_hi:[0,0,1]
	v_mov_b32_e32 v6, v10
	v_mov_b32_e32 v7, v3
	v_pk_mov_b32 v[2:3], v[2:3], v[10:11] op_sel:[1,0]
	s_nop 0
	v_pk_mul_f32 v[2:3], v[30:31], v[2:3]
	s_nop 0
	v_sub_f32_e32 v10, v2, v3
	v_pk_mul_f32 v[2:3], v[30:31], v[6:7]
	v_cvt_pk_bf16_f32 v6, v14, v10
	v_pk_mul_f32 v[10:11], v[28:29], v[12:13] op_sel:[1,0] op_sel_hi:[0,0]
	v_add_f32_e32 v2, v2, v3
	v_cvt_pk_bf16_f32 v2, v15, v2
	v_pk_fma_f32 v[14:15], v[28:29], v[8:9], v[10:11] op_sel_hi:[1,0,1]
	v_pk_fma_f32 v[10:11], v[28:29], v[8:9], v[10:11] op_sel_hi:[1,0,1] neg_lo:[0,0,1] neg_hi:[0,0,1]
	v_mov_b32_e32 v20, v14
	v_mov_b32_e32 v21, v11
	v_pk_mov_b32 v[10:11], v[10:11], v[14:15] op_sel:[1,0]
	s_nop 0
	v_pk_mul_f32 v[10:11], v[30:31], v[10:11]
	s_nop 0
	v_sub_f32_e32 v3, v10, v11
	v_pk_mul_f32 v[10:11], v[30:31], v[20:21]
	s_nop 0
	v_add_f32_e32 v14, v10, v11
	v_pk_mul_f32 v[10:11], v[28:29], v[12:13] op_sel:[1,1] op_sel_hi:[0,1]
	v_pk_fma_f32 v[12:13], v[28:29], v[8:9], v[10:11] op_sel:[0,1,0]
	v_pk_fma_f32 v[8:9], v[28:29], v[8:9], v[10:11] op_sel:[0,1,0] neg_lo:[0,0,1] neg_hi:[0,0,1]
	v_mov_b32_e32 v10, v12
	v_mov_b32_e32 v11, v9
	v_pk_mov_b32 v[8:9], v[8:9], v[12:13] op_sel:[1,0]
	s_nop 0
	v_pk_mul_f32 v[8:9], v[30:31], v[8:9]
	s_nop 0
	v_sub_f32_e32 v7, v8, v9
	v_pk_mul_f32 v[8:9], v[30:31], v[10:11]
	v_cvt_pk_bf16_f32 v7, v3, v7
	s_nop 0
	v_add_f32_e32 v8, v8, v9
	v_cvt_pk_bf16_f32 v3, v14, v8
	global_load_dwordx4 v[8:11], v[24:25], off offset:32
	global_load_dwordx4 v[12:15], v[26:27], off offset:32
	s_waitcnt vmcnt(0)
; DEV unsigned pk_bf16(float lo, float hi) { unsigned r; asm("v_cvt_pk_bf16_f32 %0, %1, %2" : "=v"(r) : "v"(lo), "v"(hi)); return r; }
; DEV float2 cmulf(float2 a, float2 b) { return make_float2(a.x * b.x - a.y * b.y, a.x * b.y + a.y * b.x); }
; DEV void ef_item(const P& p, int l, int it) {
;     ...
; #pragma unroll
;   for (int c2 = 0; c2 < 8; ++c2) {
;     const size_t bi = ((size_t)gi * 64 + pp) * 16 + c2 * 2;
;     const float2 v0 = cmulf(wf, cmulf(f, make_float2(p.b_re[bi], p.b_im[bi])));
;     const float2 v1 = cmulf(wf, cmulf(f, make_float2(p.b_re[bi + 1], p.b_im[bi + 1])));
;     fr[c2] = pk_bf16(v0.x, v1.x); fi[c2] = pk_bf16(v0.y, v1.y);
;   }
;   u32x4* r0 = (u32x4*)(Ft + (size_t)(dir * 128 + pp * 2) * 512 + t * 16);
;   u32x4* r1 = (u32x4*)(Ft + (size_t)(dir * 128 + pp * 2 + 1) * 512 + t * 16);
;   r0[0] = (u32x4){fr[0], fr[1], fr[2], fr[3]}; r0[1] = (u32x4){fr[4], fr[5], fr[6], fr[7]};
;   r1[0] = (u32x4){fi[0], fi[1], fi[2], fi[3]}; r1[1] = (u32x4){fi[4], fi[5], fi[6], fi[7]};
	v_pk_mul_f32 v[20:21], v[28:29], v[12:13] op_sel:[1,0] op_sel_hi:[0,0]
	v_pk_fma_f32 v[22:23], v[28:29], v[8:9], v[20:21] op_sel_hi:[1,0,1]
	v_pk_fma_f32 v[20:21], v[28:29], v[8:9], v[20:21] op_sel_hi:[1,0,1] neg_lo:[0,0,1] neg_hi:[0,0,1]
	v_mov_b32_e32 v32, v22
	v_mov_b32_e32 v33, v21
	v_pk_mov_b32 v[20:21], v[20:21], v[22:23] op_sel:[1,0]
	v_pk_mul_f32 v[12:13], v[28:29], v[12:13] op_sel:[1,1] op_sel_hi:[0,1]
	v_pk_mul_f32 v[20:21], v[30:31], v[20:21]
	s_nop 0
	v_sub_f32_e32 v19, v20, v21
	v_pk_mul_f32 v[20:21], v[30:31], v[32:33]
	s_nop 0
	v_add_f32_e32 v22, v20, v21
	v_pk_fma_f32 v[20:21], v[28:29], v[8:9], v[12:13] op_sel:[0,1,0]
	v_pk_fma_f32 v[8:9], v[28:29], v[8:9], v[12:13] op_sel:[0,1,0] neg_lo:[0,0,1] neg_hi:[0,0,1]
	v_mov_b32_e32 v12, v20
	v_mov_b32_e32 v13, v9
	v_pk_mov_b32 v[8:9], v[8:9], v[20:21] op_sel:[1,0]
	s_nop 0
	v_pk_mul_f32 v[8:9], v[30:31], v[8:9]
	s_nop 0
	v_sub_f32_e32 v20, v8, v9
	v_pk_mul_f32 v[8:9], v[30:31], v[12:13]
	v_cvt_pk_bf16_f32 v12, v19, v20
	v_pk_mul_f32 v[20:21], v[28:29], v[14:15] op_sel:[1,0] op_sel_hi:[0,0]
	v_add_f32_e32 v8, v8, v9
	v_cvt_pk_bf16_f32 v8, v22, v8
	v_pk_fma_f32 v[22:23], v[28:29], v[10:11], v[20:21] op_sel_hi:[1,0,1]
	v_pk_fma_f32 v[20:21], v[28:29], v[10:11], v[20:21] op_sel_hi:[1,0,1] neg_lo:[0,0,1] neg_hi:[0,0,1]
	v_mov_b32_e32 v32, v22
	v_mov_b32_e32 v33, v21
	v_pk_mov_b32 v[20:21], v[20:21], v[22:23] op_sel:[1,0]
	v_pk_mul_f32 v[14:15], v[28:29], v[14:15] op_sel:[1,1] op_sel_hi:[0,1]
	v_pk_mul_f32 v[20:21], v[30:31], v[20:21]
	s_nop 0
	v_sub_f32_e32 v9, v20, v21
	v_pk_mul_f32 v[20:21], v[30:31], v[32:33]
	s_nop 0
	v_add_f32_e32 v19, v20, v21
	v_pk_fma_f32 v[20:21], v[28:29], v[10:11], v[14:15] op_sel:[0,1,0]
	v_pk_fma_f32 v[10:11], v[28:29], v[10:11], v[14:15] op_sel:[0,1,0] neg_lo:[0,0,1] neg_hi:[0,0,1]
	v_mov_b32_e32 v14, v20
	v_mov_b32_e32 v15, v11
	v_pk_mov_b32 v[10:11], v[10:11], v[20:21] op_sel:[1,0]
	global_load_dwordx4 v[20:23], v[24:25], off offset:48
	s_nop 0
	global_load_dwordx4 v[24:27], v[26:27], off offset:48
	v_pk_mul_f32 v[10:11], v[30:31], v[10:11]
	s_nop 0
	v_sub_f32_e32 v13, v10, v11
	v_pk_mul_f32 v[10:11], v[30:31], v[14:15]
	v_cvt_pk_bf16_f32 v13, v9, v13
	s_nop 0
	v_add_f32_e32 v10, v10, v11
	v_cvt_pk_bf16_f32 v9, v19, v10
	s_waitcnt vmcnt(0)
	v_pk_mul_f32 v[10:11], v[28:29], v[24:25] op_sel:[1,0] op_sel_hi:[0,0]
	v_pk_fma_f32 v[14:15], v[28:29], v[20:21], v[10:11] op_sel_hi:[1,0,1]
	v_pk_fma_f32 v[10:11], v[28:29], v[20:21], v[10:11] op_sel_hi:[1,0,1] neg_lo:[0,0,1] neg_hi:[0,0,1]
	v_mov_b32_e32 v32, v14
	v_mov_b32_e32 v33, v11
	v_pk_mov_b32 v[10:11], v[10:11], v[14:15] op_sel:[1,0]
	s_nop 0
	v_pk_mul_f32 v[10:11], v[30:31], v[10:11]
	s_nop 0
	v_sub_f32_e32 v19, v10, v11
	v_pk_mul_f32 v[10:11], v[30:31], v[32:33]
	s_nop 0
	v_add_f32_e32 v32, v10, v11
	v_pk_mul_f32 v[10:11], v[28:29], v[24:25] op_sel:[1,1] op_sel_hi:[0,1]
	v_pk_fma_f32 v[14:15], v[28:29], v[20:21], v[10:11] op_sel:[0,1,0]
	v_pk_fma_f32 v[10:11], v[28:29], v[20:21], v[10:11] op_sel:[0,1,0] neg_lo:[0,0,1] neg_hi:[0,0,1]
	v_mov_b32_e32 v20, v14
	v_mov_b32_e32 v21, v11
	v_pk_mov_b32 v[10:11], v[10:11], v[14:15] op_sel:[1,0]
	s_nop 0
	v_pk_mul_f32 v[10:11], v[30:31], v[10:11]
	s_nop 0
	v_sub_f32_e32 v14, v10, v11
	v_pk_mul_f32 v[10:11], v[30:31], v[20:21]
	v_pk_mul_f32 v[20:21], v[28:29], v[26:27] op_sel:[1,0] op_sel_hi:[0,0]
	v_pk_fma_f32 v[24:25], v[28:29], v[22:23], v[20:21] op_sel_hi:[1,0,1]
	v_pk_fma_f32 v[20:21], v[28:29], v[22:23], v[20:21] op_sel_hi:[1,0,1] neg_lo:[0,0,1] neg_hi:[0,0,1]
	v_add_f32_e32 v10, v10, v11
	v_mov_b32_e32 v33, v21
	v_pk_mov_b32 v[20:21], v[20:21], v[24:25] op_sel:[1,0]
	v_cvt_pk_bf16_f32 v10, v32, v10
	v_mov_b32_e32 v32, v24
	v_pk_mul_f32 v[20:21], v[30:31], v[20:21]
	v_cvt_pk_bf16_f32 v14, v19, v14
	s_nop 0
	v_sub_f32_e32 v11, v20, v21
	v_pk_mul_f32 v[20:21], v[30:31], v[32:33]
	s_nop 0
	v_add_f32_e32 v19, v20, v21
	v_pk_mul_f32 v[20:21], v[28:29], v[26:27] op_sel:[1,1] op_sel_hi:[0,1]
	v_pk_fma_f32 v[24:25], v[28:29], v[22:23], v[20:21] op_sel:[0,1,0]
	v_pk_fma_f32 v[20:21], v[28:29], v[22:23], v[20:21] op_sel:[0,1,0] neg_lo:[0,0,1] neg_hi:[0,0,1]
	v_mov_b32_e32 v22, v24
	v_mov_b32_e32 v23, v21
	v_pk_mov_b32 v[20:21], v[20:21], v[24:25] op_sel:[1,0]
	s_nop 0
	v_pk_mul_f32 v[20:21], v[30:31], v[20:21]
	s_nop 0
	v_sub_f32_e32 v15, v20, v21
	v_pk_mul_f32 v[20:21], v[30:31], v[22:23]
	v_cvt_pk_bf16_f32 v15, v11, v15
	s_nop 0
	v_add_f32_e32 v20, v20, v21
	v_cvt_pk_bf16_f32 v11, v19, v20
	v_ashrrev_i32_e32 v19, 31, v18
	v_lshlrev_b64 v[20:21], 10, v[18:19]
	v_or_b32_e32 v18, 1, v18
	v_ashrrev_i32_e32 v19, 31, v18
	v_lshl_add_u64 v[20:21], s[6:7], 0, v[20:21]
	v_lshlrev_b64 v[18:19], 10, v[18:19]
	v_lshl_add_u64 v[16:17], v[20:21], 0, v[40:41]
	v_lshl_add_u64 v[18:19], s[6:7], 0, v[18:19]
	v_lshl_add_u64 v[18:19], v[18:19], 0, v[40:41]
	global_store_dwordx4 v[16:17], v[4:7], off
	global_store_dwordx4 v[16:17], v[12:15], off offset:16
	global_store_dwordx4 v[18:19], v[0:3], off
	global_store_dwordx4 v[18:19], v[8:11], off offset:16
	s_cbranch_scc1 .LBB0_442

; DEV int get_tid() { int t; asm volatile("v_mov_b32 %0, %1" : "=v"(t) : "v"((int)(threadIdx.x & 255))); return t; }
; DEV unsigned pk_bf16(float lo, float hi) { unsigned r; asm("v_cvt_pk_bf16_f32 %0, %1, %2" : "=v"(r) : "v"(lo), "v"(hi)); return r; }
; DEV float2 cmulf(float2 a, float2 b) { return make_float2(a.x * b.x - a.y * b.y, a.x * b.y + a.y * b.x); }
; DEV Disc s5_disc(const P& p, int l, int dir, int g, int pp) {
;   Disc d; const int gi = (l * 2 + dir) * 32 + g;
;   d.dt = (double)expf(p.log_dt[gi]); d.are = p.a_re[gi * 64 + pp]; d.aim = p.a_im[gi * 64 + pp];
;   const float mag = __expf((float)(d.dt * (double)d.are)); float sn, cs; sincos_d(d.dt * (double)d.aim, sn, cs);
;   const float abr = mag * cs, abi = mag * sn, den = d.are * d.are + d.aim * d.aim, nr = abr - 1.0f, ni = abi;
;   d.fre = (nr * d.are + ni * d.aim) / den; d.fim = (ni * d.are - nr * d.aim) / den;
;   return d;
; }
; DEV float2 cpow(const Disc& d, int e) {
;   const float mag = __expf((float)((double)e * d.dt * (double)d.are)); float sn, cs; sincos_d((double)e * d.dt * (double)d.aim, sn, cs);
;   return make_float2(mag * cs, mag * sn);
; }
; DEV void ef_item(const P& p, int l, int it) {
;   const int g = it >> 4, id = (it & 15) * 256 + get_tid();
;   const int t = id & 31, pp = (id >> 5) & 63, dir = id >> 11, gi = (l * 2 + dir) * 32 + g;
;   const Disc d = s5_disc(p, l, dir, g, pp);
;   const float2 we = cpow(d, dir == 0 ? t + 1 : 32 - t), wf = cpow(d, dir == 0 ? 31 - t : t);
;   unsigned* Et = (unsigned*)(p.ws + OFF_ET) + (size_t)g * 512 * 128;
;   bf16_t* Ft = (bf16_t*)(p.ws + OFF_FT) + (size_t)g * 256 * 512;
; #pragma unroll
;   for (int c = 0; c < 16; ++c) {
;     const float2 cc = make_float2(p.c_re[((size_t)gi * 16 + c) * 64 + pp], p.c_im[((size_t)gi * 16 + c) * 64 + pp]);
;     const float2 cw = cmulf(cc, we);
;     Et[(size_t)(t * 16 + c) * 128 + dir * 64 + pp] = pk_bf16(cw.x, -cw.y);
;   }
.LBB0_1199:
	s_and_b32 s1, s6, 0xf00
	v_mov_b32 v19, v238
	s_ashr_i32 s0, s33, 4
	v_add_u32_e32 v12, s1, v19
	v_ashrrev_i32_e32 v18, 11, v12
	v_lshlrev_b32_e32 v0, 5, v18
	v_ashrrev_i32_e32 v1, 31, v0
	s_ashr_i32 s1, s0, 31
	v_add3_u32 v4, s0, 64, v0
	v_lshl_add_u64 v[0:1], s[0:1], 0, v[0:1]
	v_lshl_add_u64 v[0:1], v[0:1], 2, s[62:63]
	global_load_dword v0, v[0:1], off offset:256
	v_bfe_u32 v17, v12, 5, 6
	v_and_b32_e32 v16, 31, v19
	v_ashrrev_i32_e32 v5, 31, v4
	s_lshl_b64 s[0:1], s[0:1], 18
	s_add_u32 s8, s2, s0
	s_addc_u32 s9, s3, s1
	v_lshlrev_b32_e32 v40, 2, v17
	s_add_u32 s0, s4, s0
	s_addc_u32 s1, s5, s1
	s_add_i32 s33, s33, s79
	s_add_i32 s6, s6, s7
	s_cmpk_lt_i32 s33, 0x200
	s_waitcnt vmcnt(0)
	v_mul_f32_e32 v1, 0x3fb8aa3b, v0
	v_fma_f32 v2, v0, s15, -v1
	v_rndne_f32_e32 v3, v1
	v_fmac_f32_e32 v2, 0x32a5705f, v0
	v_sub_f32_e32 v1, v1, v3
	v_add_f32_e32 v1, v1, v2
	v_exp_f32_e32 v1, v1
	v_cvt_i32_f32_e32 v2, v3
	v_cmp_ngt_f32_e32 vcc, s16, v0
	v_ldexp_f32 v1, v1, v2
	s_nop 0
	v_cndmask_b32_e32 v1, 0, v1, vcc
	v_cmp_nlt_f32_e32 vcc, s17, v0
	v_lshl_or_b32 v0, v4, 6, v17
	v_lshlrev_b64 v[4:5], 10, v[4:5]
	v_cndmask_b32_e32 v8, v236, v1, vcc
	v_ashrrev_i32_e32 v1, 31, v0
	v_lshlrev_b64 v[2:3], 2, v[0:1]
	v_lshl_add_u64 v[0:1], s[58:59], 0, v[2:3]
	global_load_dword v0, v[0:1], off
	v_lshl_add_u64 v[2:3], s[60:61], 0, v[2:3]
	global_load_dword v1, v[2:3], off
	v_cvt_f64_f32_e32 v[6:7], v8
	v_cmp_gt_u32_e32 vcc, s18, v12
	s_waitcnt vmcnt(1)
	v_mul_f32_e32 v2, v8, v0
	v_mul_f32_e32 v2, 0x3fb8aa3b, v2
	s_waitcnt vmcnt(0)
	v_cvt_f64_f32_e32 v[8:9], v1
	v_exp_f32_e32 v13, v2
	v_mul_f64 v[2:3], v[6:7], v[8:9]
	v_mul_f64 v[10:11], v[2:3], s[10:11]
	v_rndne_f64_e32 v[10:11], v[10:11]
	v_fmac_f64_e32 v[2:3], s[12:13], v[10:11]
	v_mul_f64 v[2:3], v[2:3], s[10:11]
	v_cvt_f32_f64_e32 v2, v[2:3]
	v_sin_f32_e32 v3, v2
	v_cos_f32_e32 v10, v2
	v_sub_u32_e32 v11, 32, v16
	v_mul_f32_e32 v2, v13, v3
	v_fma_f32 v3, v13, v10, -1.0
	v_add_u32_e32 v10, 1, v16
	v_cndmask_b32_e32 v10, v11, v10, vcc
	v_cvt_f64_u32_e32 v[10:11], v10
	v_mul_f64 v[12:13], v[6:7], v[10:11]
	v_cvt_f64_f32_e32 v[10:11], v0
	v_mul_f64 v[14:15], v[12:13], v[10:11]
	v_cvt_f32_f64_e32 v14, v[14:15]
	v_mul_f32_e32 v14, 0x3fb8aa3b, v14
	v_mul_f64 v[12:13], v[12:13], v[8:9]
	v_exp_f32_e32 v20, v14
	v_mul_f64 v[14:15], v[12:13], s[10:11]
	v_rndne_f64_e32 v[14:15], v[14:15]
	v_fmac_f64_e32 v[12:13], s[12:13], v[14:15]
	v_bitop3_b32 v14, v19, 31, v19 bitop3:0xc
	v_cndmask_b32_e32 v14, v16, v14, vcc
	v_cvt_f64_u32_e32 v[14:15], v14
	v_mul_f64 v[12:13], v[12:13], s[10:11]
	v_mul_f64 v[14:15], v[6:7], v[14:15]
	v_cvt_f32_f64_e32 v12, v[12:13]
	v_mul_f64 v[8:9], v[14:15], v[8:9]
	v_sin_f32_e32 v13, v12
	v_cos_f32_e32 v12, v12
	v_mul_f64 v[6:7], v[14:15], v[10:11]
	v_mul_f64 v[10:11], v[8:9], s[10:11]
	v_rndne_f64_e32 v[10:11], v[10:11]
	v_fmac_f64_e32 v[8:9], s[12:13], v[10:11]
	v_or_b32_e32 v10, v4, v17
	v_mov_b32_e32 v11, v5
	v_lshlrev_b64 v[10:11], 2, v[10:11]
	v_mul_f32_e32 v12, v20, v12
	v_mul_f32_e32 v13, v20, v13
	v_lshl_add_u64 v[20:21], s[68:69], 0, v[10:11]
	v_lshl_add_u64 v[10:11], s[70:71], 0, v[10:11]
	v_mul_f64 v[8:9], v[8:9], s[10:11]
	global_load_dword v19, v[10:11], off
	v_cvt_f32_f64_e32 v6, v[6:7]
	v_cvt_f32_f64_e32 v7, v[8:9]
	global_load_dword v9, v[20:21], off
	v_lshlrev_b32_e32 v14, 6, v18
	v_ashrrev_i32_e32 v15, 31, v14
	v_lshl_add_u64 v[14:15], v[14:15], 2, s[8:9]
	v_lshl_add_u64 v[14:15], v[14:15], 0, v[40:41]
	v_lshlrev_b32_e32 v40, 13, v16
	v_lshl_add_u64 v[14:15], v[14:15], 0, v[40:41]
	v_lshl_or_b32 v4, v17, 4, v4
	v_lshlrev_b64 v[4:5], 2, v[4:5]
	v_lshl_add_u64 v[26:27], s[66:67], 0, v[4:5]
	v_lshl_add_u64 v[24:25], s[64:65], 0, v[4:5]
	v_mov_b32_e32 v4, v1
	v_pk_mul_f32 v[4:5], v[4:5], v[2:3] op_sel:[0,1] op_sel_hi:[0,0]
	v_pk_fma_f32 v[28:29], v[0:1], v[2:3], v[4:5] neg_lo:[0,0,1] neg_hi:[0,0,1]
	v_cos_f32_e32 v8, v7
	v_mul_f32_e32 v6, 0x3fb8aa3b, v6
	v_exp_f32_e32 v6, v6
	v_lshlrev_b32_e32 v18, 7, v18
	v_lshl_or_b32 v18, v17, 1, v18
	v_lshlrev_b32_e32 v40, 5, v16
	s_waitcnt vmcnt(1)
	v_mul_f32_e32 v22, v19, v13
	v_mul_f32_e32 v19, v19, v12
	s_waitcnt vmcnt(0)
	v_fmac_f32_e32 v19, v9, v13
	v_fma_f32 v22, v9, v12, -v22
	v_xor_b32_e32 v9, 0x80000000, v19
	v_cvt_pk_bf16_f32 v9, v22, v9
	global_store_dword v[14:15], v9, off
	global_load_dword v102, v[20:21], off offset:256
	global_load_dword v103, v[10:11], off offset:256
	global_load_dword v104, v[20:21], off offset:512
	global_load_dword v105, v[10:11], off offset:512
	global_load_dword v106, v[20:21], off offset:768
	global_load_dword v107, v[10:11], off offset:768
	global_load_dword v108, v[20:21], off offset:1024
	global_load_dword v109, v[10:11], off offset:1024
	global_load_dword v110, v[20:21], off offset:1280
	global_load_dword v111, v[10:11], off offset:1280
	global_load_dword v112, v[20:21], off offset:1536
	global_load_dword v113, v[10:11], off offset:1536
	global_load_dword v114, v[20:21], off offset:1792
	global_load_dword v115, v[10:11], off offset:1792
	global_load_dword v116, v[20:21], off offset:2048
	global_load_dword v117, v[10:11], off offset:2048
	global_load_dword v118, v[20:21], off offset:2304
	global_load_dword v119, v[10:11], off offset:2304
	global_load_dword v120, v[20:21], off offset:2560
	global_load_dword v121, v[10:11], off offset:2560
	global_load_dword v122, v[20:21], off offset:2816
	global_load_dword v123, v[10:11], off offset:2816
	global_load_dword v124, v[20:21], off offset:3072
	global_load_dword v125, v[10:11], off offset:3072
	global_load_dword v126, v[20:21], off offset:3328
	global_load_dword v127, v[10:11], off offset:3328
	global_load_dword v128, v[20:21], off offset:3584
	global_load_dword v129, v[10:11], off offset:3584
	global_load_dword v130, v[20:21], off offset:3840
	global_load_dword v131, v[10:11], off offset:3840
	s_waitcnt vmcnt(28)
; DEV unsigned pk_bf16(float lo, float hi) { unsigned r; asm("v_cvt_pk_bf16_f32 %0, %1, %2" : "=v"(r) : "v"(lo), "v"(hi)); return r; }
; DEV float2 cmulf(float2 a, float2 b) { return make_float2(a.x * b.x - a.y * b.y, a.x * b.y + a.y * b.x); }
; DEV Disc s5_disc(const P& p, int l, int dir, int g, int pp) {
;     ...
;   const float abr = mag * cs, abi = mag * sn, den = d.are * d.are + d.aim * d.aim, nr = abr - 1.0f, ni = abi;
;   d.fre = (nr * d.are + ni * d.aim) / den; d.fim = (ni * d.are - nr * d.aim) / den;
; DEV void ef_item(const P& p, int l, int it) {
;     ...
;   for (int c = 0; c < 16; ++c) {
;     const float2 cc = make_float2(p.c_re[((size_t)gi * 16 + c) * 64 + pp], p.c_im[((size_t)gi * 16 + c) * 64 + pp]);
;     const float2 cw = cmulf(cc, we);
;     Et[(size_t)(t * 16 + c) * 128 + dir * 64 + pp] = pk_bf16(cw.x, -cw.y);
;   }
;   const float2 f = make_float2(d.fre, d.fim);
;   unsigned fr[8], fi[8];
; #pragma unroll
;   for (int c2 = 0; c2 < 8; ++c2) {
;     const size_t bi = ((size_t)gi * 64 + pp) * 16 + c2 * 2;
;     const float2 v0 = cmulf(wf, cmulf(f, make_float2(p.b_re[bi], p.b_im[bi])));
;     const float2 v1 = cmulf(wf, cmulf(f, make_float2(p.b_re[bi + 1], p.b_im[bi + 1])));
;     fr[c2] = pk_bf16(v0.x, v1.x); fi[c2] = pk_bf16(v0.y, v1.y);
	v_mul_f32_e32 v22, v103, v13
	v_mul_f32_e32 v19, v103, v12
	v_fmac_f32_e32 v19, v102, v13
	v_fma_f32 v22, v102, v12, -v22
	v_xor_b32_e32 v9, 0x80000000, v19
	v_cvt_pk_bf16_f32 v9, v22, v9
	global_store_dword v[14:15], v9, off offset:512
	s_waitcnt vmcnt(27)
	v_mul_f32_e32 v22, v105, v13
	v_mul_f32_e32 v19, v105, v12
	v_fmac_f32_e32 v19, v104, v13
	v_fma_f32 v22, v104, v12, -v22
	v_xor_b32_e32 v9, 0x80000000, v19
	v_cvt_pk_bf16_f32 v9, v22, v9
	global_store_dword v[14:15], v9, off offset:1024
	s_waitcnt vmcnt(26)
	v_mul_f32_e32 v22, v13, v107
	v_mul_f32_e32 v19, v12, v107
	v_fmac_f32_e32 v19, v13, v106
	v_fma_f32 v22, v12, v106, -v22
	v_xor_b32_e32 v9, 0x80000000, v19
	v_cvt_pk_bf16_f32 v9, v22, v9
	global_store_dword v[14:15], v9, off offset:1536
	s_waitcnt vmcnt(25)
	v_mul_f32_e32 v22, v13, v109
	v_mul_f32_e32 v19, v12, v109
	v_fmac_f32_e32 v19, v13, v108
	v_fma_f32 v22, v12, v108, -v22
	v_xor_b32_e32 v9, 0x80000000, v19
	v_cvt_pk_bf16_f32 v9, v22, v9
	global_store_dword v[14:15], v9, off offset:2048
	s_waitcnt vmcnt(24)
	v_mul_f32_e32 v22, v13, v111
	v_mul_f32_e32 v19, v12, v111
	v_fmac_f32_e32 v19, v13, v110
	v_fma_f32 v22, v12, v110, -v22
	v_xor_b32_e32 v9, 0x80000000, v19
	v_cvt_pk_bf16_f32 v9, v22, v9
	global_store_dword v[14:15], v9, off offset:2560
	s_waitcnt vmcnt(23)
	v_mul_f32_e32 v22, v13, v113
	v_mul_f32_e32 v19, v12, v113
	v_fmac_f32_e32 v19, v13, v112
	v_fma_f32 v22, v12, v112, -v22
	v_xor_b32_e32 v9, 0x80000000, v19
	v_cvt_pk_bf16_f32 v9, v22, v9
	global_store_dword v[14:15], v9, off offset:3072
	s_waitcnt vmcnt(22)
	v_mul_f32_e32 v22, v13, v115
	v_mul_f32_e32 v19, v12, v115
	v_fmac_f32_e32 v19, v13, v114
	v_fma_f32 v22, v12, v114, -v22
	v_xor_b32_e32 v9, 0x80000000, v19
	v_cvt_pk_bf16_f32 v9, v22, v9
	global_store_dword v[14:15], v9, off offset:3584
	v_add_co_u32_e32 v14, vcc, s14, v14
	s_waitcnt vmcnt(21)
	v_mul_f32_e32 v22, v13, v117
	v_mul_f32_e32 v19, v12, v117
	v_fmac_f32_e32 v19, v13, v116
	v_fma_f32 v22, v12, v116, -v22
	v_xor_b32_e32 v9, 0x80000000, v19
	v_addc_co_u32_e32 v15, vcc, 0, v15, vcc
	v_cvt_pk_bf16_f32 v9, v22, v9
	global_store_dword v[14:15], v9, off
	s_waitcnt vmcnt(20)
	v_mul_f32_e32 v22, v13, v119
	v_mul_f32_e32 v19, v12, v119
	v_fmac_f32_e32 v19, v13, v118
	v_fma_f32 v22, v12, v118, -v22
	v_xor_b32_e32 v9, 0x80000000, v19
	v_cvt_pk_bf16_f32 v9, v22, v9
	global_store_dword v[14:15], v9, off offset:512
	s_waitcnt vmcnt(19)
	v_mul_f32_e32 v22, v13, v121
	v_mul_f32_e32 v19, v12, v121
	v_fmac_f32_e32 v19, v13, v120
	v_fma_f32 v22, v12, v120, -v22
	v_xor_b32_e32 v9, 0x80000000, v19
	v_cvt_pk_bf16_f32 v9, v22, v9
	global_store_dword v[14:15], v9, off offset:1024
	s_waitcnt vmcnt(18)
	v_mul_f32_e32 v22, v13, v123
	v_mul_f32_e32 v19, v12, v123
	v_fmac_f32_e32 v19, v13, v122
	v_fma_f32 v22, v12, v122, -v22
	v_xor_b32_e32 v9, 0x80000000, v19
	v_cvt_pk_bf16_f32 v9, v22, v9
	global_store_dword v[14:15], v9, off offset:1536
	s_waitcnt vmcnt(17)
	v_mul_f32_e32 v22, v13, v125
	v_mul_f32_e32 v19, v12, v125
	v_fmac_f32_e32 v19, v13, v124
	v_fma_f32 v22, v12, v124, -v22
	v_xor_b32_e32 v9, 0x80000000, v19
	v_cvt_pk_bf16_f32 v9, v22, v9
	global_store_dword v[14:15], v9, off offset:2048
	s_waitcnt vmcnt(16)
	v_mul_f32_e32 v22, v13, v127
	v_mul_f32_e32 v19, v12, v127
	v_fmac_f32_e32 v19, v13, v126
	v_fma_f32 v22, v12, v126, -v22
	v_xor_b32_e32 v9, 0x80000000, v19
	v_cvt_pk_bf16_f32 v9, v22, v9
	global_store_dword v[14:15], v9, off offset:2560
	s_waitcnt vmcnt(15)
	v_mul_f32_e32 v22, v13, v129
	v_mul_f32_e32 v19, v12, v129
	v_fmac_f32_e32 v19, v13, v128
	v_fma_f32 v22, v12, v128, -v22
	v_xor_b32_e32 v9, 0x80000000, v19
	v_cvt_pk_bf16_f32 v9, v22, v9
	global_store_dword v[14:15], v9, off offset:3072
	s_waitcnt vmcnt(14)
	v_mul_f32_e32 v11, v13, v131
	v_mul_f32_e32 v10, v12, v131
	v_fmac_f32_e32 v10, v13, v130
	v_fma_f32 v11, v12, v130, -v11
	v_xor_b32_e32 v9, 0x80000000, v10
	v_cvt_pk_bf16_f32 v9, v11, v9
	global_store_dword v[14:15], v9, off offset:3584
	global_load_dwordx4 v[20:23], v[26:27], off
	global_load_dwordx4 v[10:13], v[24:25], off
	v_pk_mul_f32 v[14:15], v[0:1], v[0:1]
	v_pk_fma_f32 v[0:1], v[0:1], v[2:3], v[4:5] op_sel_hi:[0,1,1]
	v_pk_add_f32 v[2:3], v[14:15], v[14:15] op_sel:[0,1] op_sel_hi:[0,1]
	v_div_scale_f32 v0, s[8:9], v3, v3, v1
	v_rcp_f32_e32 v4, v0
	v_sin_f32_e32 v9, v7
	v_fma_f32 v5, -v0, v4, 1.0
	v_fmac_f32_e32 v4, v5, v4
	v_div_scale_f32 v5, vcc, v1, v3, v1
	v_mul_f32_e32 v7, v5, v4
	v_fma_f32 v14, -v0, v7, v5
	v_fmac_f32_e32 v7, v14, v4
	v_fma_f32 v0, -v0, v7, v5
	v_div_fmas_f32 v0, v0, v4, v7
	v_div_fixup_f32 v29, v0, v3, v1
	v_div_scale_f32 v0, s[8:9], v2, v2, v28
	v_rcp_f32_e32 v1, v0
	v_pk_mul_f32 v[30:31], v[6:7], v[8:9] op_sel_hi:[0,1]
	v_fma_f32 v3, -v0, v1, 1.0
	v_fmac_f32_e32 v1, v3, v1
	v_div_scale_f32 v3, vcc, v28, v2, v28
	v_mul_f32_e32 v4, v3, v1
	v_fma_f32 v5, -v0, v4, v3
	v_fmac_f32_e32 v4, v5, v1
	v_fma_f32 v0, -v0, v4, v3
	v_div_fmas_f32 v0, v0, v1, v4
	v_div_fixup_f32 v28, v0, v2, v28
	s_waitcnt vmcnt(1)
	v_pk_mul_f32 v[0:1], v[28:29], v[20:21] op_sel:[1,0] op_sel_hi:[0,0]
	s_waitcnt vmcnt(0)
; DEV unsigned pk_bf16(float lo, float hi) { unsigned r; asm("v_cvt_pk_bf16_f32 %0, %1, %2" : "=v"(r) : "v"(lo), "v"(hi)); return r; }
; DEV float2 cmulf(float2 a, float2 b) { return make_float2(a.x * b.x - a.y * b.y, a.x * b.y + a.y * b.x); }
; DEV void ef_item(const P& p, int l, int it) {
;     ...
; #pragma unroll
;   for (int c2 = 0; c2 < 8; ++c2) {
;     const size_t bi = ((size_t)gi * 64 + pp) * 16 + c2 * 2;
;     const float2 v0 = cmulf(wf, cmulf(f, make_float2(p.b_re[bi], p.b_im[bi])));
;     const float2 v1 = cmulf(wf, cmulf(f, make_float2(p.b_re[bi + 1], p.b_im[bi + 1])));
;     fr[c2] = pk_bf16(v0.x, v1.x); fi[c2] = pk_bf16(v0.y, v1.y);
;   }
	v_pk_fma_f32 v[2:3], v[28:29], v[10:11], v[0:1] op_sel_hi:[1,0,1]
	v_pk_fma_f32 v[0:1], v[28:29], v[10:11], v[0:1] op_sel_hi:[1,0,1] neg_lo:[0,0,1] neg_hi:[0,0,1]
	v_mov_b32_e32 v4, v2
	v_mov_b32_e32 v5, v1
	v_pk_mov_b32 v[0:1], v[0:1], v[2:3] op_sel:[1,0]
	s_nop 0
	v_pk_mul_f32 v[0:1], v[30:31], v[0:1]
	s_nop 0
	v_sub_f32_e32 v6, v0, v1
	v_pk_mul_f32 v[0:1], v[30:31], v[4:5]
	s_nop 0
	v_add_f32_e32 v7, v0, v1
	v_pk_mul_f32 v[0:1], v[28:29], v[20:21] op_sel:[1,1] op_sel_hi:[0,1]
	v_pk_fma_f32 v[2:3], v[28:29], v[10:11], v[0:1] op_sel:[0,1,0]
	v_pk_fma_f32 v[0:1], v[28:29], v[10:11], v[0:1] op_sel:[0,1,0] neg_lo:[0,0,1] neg_hi:[0,0,1]
	v_mov_b32_e32 v4, v2
	v_mov_b32_e32 v5, v1
	v_pk_mov_b32 v[0:1], v[0:1], v[2:3] op_sel:[1,0]
	s_nop 0
	v_pk_mul_f32 v[0:1], v[30:31], v[0:1]
	s_nop 0
	v_sub_f32_e32 v2, v0, v1
	v_pk_mul_f32 v[0:1], v[30:31], v[4:5]
	v_cvt_pk_bf16_f32 v4, v6, v2
	v_pk_mul_f32 v[2:3], v[28:29], v[22:23] op_sel:[1,0] op_sel_hi:[0,0]
	v_add_f32_e32 v0, v0, v1
	v_cvt_pk_bf16_f32 v0, v7, v0
	v_pk_fma_f32 v[6:7], v[28:29], v[12:13], v[2:3] op_sel_hi:[1,0,1]
	v_pk_fma_f32 v[2:3], v[28:29], v[12:13], v[2:3] op_sel_hi:[1,0,1] neg_lo:[0,0,1] neg_hi:[0,0,1]
	v_mov_b32_e32 v8, v6
	v_mov_b32_e32 v9, v3
	v_pk_mov_b32 v[2:3], v[2:3], v[6:7] op_sel:[1,0]
	s_nop 0
	v_pk_mul_f32 v[2:3], v[30:31], v[2:3]
	s_nop 0
	v_sub_f32_e32 v1, v2, v3
	v_pk_mul_f32 v[2:3], v[30:31], v[8:9]
	s_nop 0
	v_add_f32_e32 v10, v2, v3
	v_pk_mul_f32 v[2:3], v[28:29], v[22:23] op_sel:[1,1] op_sel_hi:[0,1]
	v_pk_fma_f32 v[6:7], v[28:29], v[12:13], v[2:3] op_sel:[0,1,0]
	v_pk_fma_f32 v[2:3], v[28:29], v[12:13], v[2:3] op_sel:[0,1,0] neg_lo:[0,0,1] neg_hi:[0,0,1]
	v_mov_b32_e32 v8, v6
	v_mov_b32_e32 v9, v3
	v_pk_mov_b32 v[2:3], v[2:3], v[6:7] op_sel:[1,0]
	s_nop 0
	v_pk_mul_f32 v[2:3], v[30:31], v[2:3]
	s_nop 0
	v_sub_f32_e32 v5, v2, v3
	v_pk_mul_f32 v[2:3], v[30:31], v[8:9]
	v_cvt_pk_bf16_f32 v5, v1, v5
	s_nop 0
	v_add_f32_e32 v2, v2, v3
	v_cvt_pk_bf16_f32 v1, v10, v2
	global_load_dwordx4 v[6:9], v[24:25], off offset:16
	global_load_dwordx4 v[10:13], v[26:27], off offset:16
	s_waitcnt vmcnt(0)
	v_pk_mul_f32 v[2:3], v[28:29], v[10:11] op_sel:[1,0] op_sel_hi:[0,0]
	v_pk_fma_f32 v[14:15], v[28:29], v[6:7], v[2:3] op_sel_hi:[1,0,1]
	v_pk_fma_f32 v[2:3], v[28:29], v[6:7], v[2:3] op_sel_hi:[1,0,1] neg_lo:[0,0,1] neg_hi:[0,0,1]
	v_mov_b32_e32 v20, v14
	v_mov_b32_e32 v21, v3
	v_pk_mov_b32 v[2:3], v[2:3], v[14:15] op_sel:[1,0]
	s_nop 0
	v_pk_mul_f32 v[2:3], v[30:31], v[2:3]
	s_nop 0
	v_sub_f32_e32 v14, v2, v3
	v_pk_mul_f32 v[2:3], v[30:31], v[20:21]
	s_nop 0
	v_add_f32_e32 v15, v2, v3
	v_pk_mul_f32 v[2:3], v[28:29], v[10:11] op_sel:[1,1] op_sel_hi:[0,1]
	v_pk_fma_f32 v[10:11], v[28:29], v[6:7], v[2:3] op_sel:[0,1,0]
	v_pk_fma_f32 v[2:3], v[28:29], v[6:7], v[2:3] op_sel:[0,1,0] neg_lo:[0,0,1] neg_hi:[0,0,1]
	v_mov_b32_e32 v6, v10
	v_mov_b32_e32 v7, v3
	v_pk_mov_b32 v[2:3], v[2:3], v[10:11] op_sel:[1,0]
	s_nop 0
	v_pk_mul_f32 v[2:3], v[30:31], v[2:3]
	s_nop 0
	v_sub_f32_e32 v10, v2, v3
	v_pk_mul_f32 v[2:3], v[30:31], v[6:7]
	v_cvt_pk_bf16_f32 v6, v14, v10
	v_pk_mul_f32 v[10:11], v[28:29], v[12:13] op_sel:[1,0] op_sel_hi:[0,0]
	v_add_f32_e32 v2, v2, v3
	v_cvt_pk_bf16_f32 v2, v15, v2
	v_pk_fma_f32 v[14:15], v[28:29], v[8:9], v[10:11] op_sel_hi:[1,0,1]
	v_pk_fma_f32 v[10:11], v[28:29], v[8:9], v[10:11] op_sel_hi:[1,0,1] neg_lo:[0,0,1] neg_hi:[0,0,1]
	v_mov_b32_e32 v20, v14
	v_mov_b32_e32 v21, v11
	v_pk_mov_b32 v[10:11], v[10:11], v[14:15] op_sel:[1,0]
	s_nop 0
	v_pk_mul_f32 v[10:11], v[30:31], v[10:11]
	s_nop 0
	v_sub_f32_e32 v3, v10, v11
	v_pk_mul_f32 v[10:11], v[30:31], v[20:21]
	s_nop 0
	v_add_f32_e32 v14, v10, v11
	v_pk_mul_f32 v[10:11], v[28:29], v[12:13] op_sel:[1,1] op_sel_hi:[0,1]
	v_pk_fma_f32 v[12:13], v[28:29], v[8:9], v[10:11] op_sel:[0,1,0]
	v_pk_fma_f32 v[8:9], v[28:29], v[8:9], v[10:11] op_sel:[0,1,0] neg_lo:[0,0,1] neg_hi:[0,0,1]
	v_mov_b32_e32 v10, v12
	v_mov_b32_e32 v11, v9
	v_pk_mov_b32 v[8:9], v[8:9], v[12:13] op_sel:[1,0]
	s_nop 0
	v_pk_mul_f32 v[8:9], v[30:31], v[8:9]
	s_nop 0
	v_sub_f32_e32 v7, v8, v9
	v_pk_mul_f32 v[8:9], v[30:31], v[10:11]
	v_cvt_pk_bf16_f32 v7, v3, v7
	s_nop 0
	v_add_f32_e32 v8, v8, v9
	v_cvt_pk_bf16_f32 v3, v14, v8
	global_load_dwordx4 v[8:11], v[24:25], off offset:32
	global_load_dwordx4 v[12:15], v[26:27], off offset:32
	s_waitcnt vmcnt(0)
; DEV unsigned pk_bf16(float lo, float hi) { unsigned r; asm("v_cvt_pk_bf16_f32 %0, %1, %2" : "=v"(r) : "v"(lo), "v"(hi)); return r; }
; DEV float2 cmulf(float2 a, float2 b) { return make_float2(a.x * b.x - a.y * b.y, a.x * b.y + a.y * b.x); }
; DEV void ef_item(const P& p, int l, int it) {
;     ...
; #pragma unroll
;   for (int c2 = 0; c2 < 8; ++c2) {
;     const size_t bi = ((size_t)gi * 64 + pp) * 16 + c2 * 2;
;     const float2 v0 = cmulf(wf, cmulf(f, make_float2(p.b_re[bi], p.b_im[bi])));
;     const float2 v1 = cmulf(wf, cmulf(f, make_float2(p.b_re[bi + 1], p.b_im[bi + 1])));
;     fr[c2] = pk_bf16(v0.x, v1.x); fi[c2] = pk_bf16(v0.y, v1.y);
;   }
;   u32x4* r0 = (u32x4*)(Ft + (size_t)(dir * 128 + pp * 2) * 512 + t * 16);
;   u32x4* r1 = (u32x4*)(Ft + (size_t)(dir * 128 + pp * 2 + 1) * 512 + t * 16);
;   r0[0] = (u32x4){fr[0], fr[1], fr[2], fr[3]}; r0[1] = (u32x4){fr[4], fr[5], fr[6], fr[7]};
;   r1[0] = (u32x4){fi[0], fi[1], fi[2], fi[3]}; r1[1] = (u32x4){fi[4], fi[5], fi[6], fi[7]};
	v_pk_mul_f32 v[20:21], v[28:29], v[12:13] op_sel:[1,0] op_sel_hi:[0,0]
	v_pk_fma_f32 v[22:23], v[28:29], v[8:9], v[20:21] op_sel_hi:[1,0,1]
	v_pk_fma_f32 v[20:21], v[28:29], v[8:9], v[20:21] op_sel_hi:[1,0,1] neg_lo:[0,0,1] neg_hi:[0,0,1]
	v_mov_b32_e32 v32, v22
	v_mov_b32_e32 v33, v21
	v_pk_mov_b32 v[20:21], v[20:21], v[22:23] op_sel:[1,0]
	v_pk_mul_f32 v[12:13], v[28:29], v[12:13] op_sel:[1,1] op_sel_hi:[0,1]
	v_pk_mul_f32 v[20:21], v[30:31], v[20:21]
	s_nop 0
	v_sub_f32_e32 v19, v20, v21
	v_pk_mul_f32 v[20:21], v[30:31], v[32:33]
	s_nop 0
	v_add_f32_e32 v22, v20, v21
	v_pk_fma_f32 v[20:21], v[28:29], v[8:9], v[12:13] op_sel:[0,1,0]
	v_pk_fma_f32 v[8:9], v[28:29], v[8:9], v[12:13] op_sel:[0,1,0] neg_lo:[0,0,1] neg_hi:[0,0,1]
	v_mov_b32_e32 v12, v20
	v_mov_b32_e32 v13, v9
	v_pk_mov_b32 v[8:9], v[8:9], v[20:21] op_sel:[1,0]
	s_nop 0
	v_pk_mul_f32 v[8:9], v[30:31], v[8:9]
	s_nop 0
	v_sub_f32_e32 v20, v8, v9
	v_pk_mul_f32 v[8:9], v[30:31], v[12:13]
	v_cvt_pk_bf16_f32 v12, v19, v20
	v_pk_mul_f32 v[20:21], v[28:29], v[14:15] op_sel:[1,0] op_sel_hi:[0,0]
	v_add_f32_e32 v8, v8, v9
	v_cvt_pk_bf16_f32 v8, v22, v8
	v_pk_fma_f32 v[22:23], v[28:29], v[10:11], v[20:21] op_sel_hi:[1,0,1]
	v_pk_fma_f32 v[20:21], v[28:29], v[10:11], v[20:21] op_sel_hi:[1,0,1] neg_lo:[0,0,1] neg_hi:[0,0,1]
	v_mov_b32_e32 v32, v22
	v_mov_b32_e32 v33, v21
	v_pk_mov_b32 v[20:21], v[20:21], v[22:23] op_sel:[1,0]
	v_pk_mul_f32 v[14:15], v[28:29], v[14:15] op_sel:[1,1] op_sel_hi:[0,1]
	v_pk_mul_f32 v[20:21], v[30:31], v[20:21]
	s_nop 0
	v_sub_f32_e32 v9, v20, v21
	v_pk_mul_f32 v[20:21], v[30:31], v[32:33]
	s_nop 0
	v_add_f32_e32 v19, v20, v21
	v_pk_fma_f32 v[20:21], v[28:29], v[10:11], v[14:15] op_sel:[0,1,0]
	v_pk_fma_f32 v[10:11], v[28:29], v[10:11], v[14:15] op_sel:[0,1,0] neg_lo:[0,0,1] neg_hi:[0,0,1]
	v_mov_b32_e32 v14, v20
	v_mov_b32_e32 v15, v11
	v_pk_mov_b32 v[10:11], v[10:11], v[20:21] op_sel:[1,0]
	global_load_dwordx4 v[20:23], v[24:25], off offset:48
	s_nop 0
	global_load_dwordx4 v[24:27], v[26:27], off offset:48
	v_pk_mul_f32 v[10:11], v[30:31], v[10:11]
	s_nop 0
	v_sub_f32_e32 v13, v10, v11
	v_pk_mul_f32 v[10:11], v[30:31], v[14:15]
	v_cvt_pk_bf16_f32 v13, v9, v13
	s_nop 0
	v_add_f32_e32 v10, v10, v11
	v_cvt_pk_bf16_f32 v9, v19, v10
	s_waitcnt vmcnt(0)
	v_pk_mul_f32 v[10:11], v[28:29], v[24:25] op_sel:[1,0] op_sel_hi:[0,0]
	v_pk_fma_f32 v[14:15], v[28:29], v[20:21], v[10:11] op_sel_hi:[1,0,1]
	v_pk_fma_f32 v[10:11], v[28:29], v[20:21], v[10:11] op_sel_hi:[1,0,1] neg_lo:[0,0,1] neg_hi:[0,0,1]
	v_mov_b32_e32 v32, v14
	v_mov_b32_e32 v33, v11
	v_pk_mov_b32 v[10:11], v[10:11], v[14:15] op_sel:[1,0]
	s_nop 0
	v_pk_mul_f32 v[10:11], v[30:31], v[10:11]
	s_nop 0
	v_sub_f32_e32 v19, v10, v11
	v_pk_mul_f32 v[10:11], v[30:31], v[32:33]
	s_nop 0
	v_add_f32_e32 v32, v10, v11
	v_pk_mul_f32 v[10:11], v[28:29], v[24:25] op_sel:[1,1] op_sel_hi:[0,1]
	v_pk_fma_f32 v[14:15], v[28:29], v[20:21], v[10:11] op_sel:[0,1,0]
	v_pk_fma_f32 v[10:11], v[28:29], v[20:21], v[10:11] op_sel:[0,1,0] neg_lo:[0,0,1] neg_hi:[0,0,1]
	v_mov_b32_e32 v20, v14
	v_mov_b32_e32 v21, v11
	v_pk_mov_b32 v[10:11], v[10:11], v[14:15] op_sel:[1,0]
	s_nop 0
	v_pk_mul_f32 v[10:11], v[30:31], v[10:11]
	s_nop 0
	v_sub_f32_e32 v14, v10, v11
	v_pk_mul_f32 v[10:11], v[30:31], v[20:21]
	v_pk_mul_f32 v[20:21], v[28:29], v[26:27] op_sel:[1,0] op_sel_hi:[0,0]
	v_pk_fma_f32 v[24:25], v[28:29], v[22:23], v[20:21] op_sel_hi:[1,0,1]
	v_pk_fma_f32 v[20:21], v[28:29], v[22:23], v[20:21] op_sel_hi:[1,0,1] neg_lo:[0,0,1] neg_hi:[0,0,1]
	v_add_f32_e32 v10, v10, v11
	v_mov_b32_e32 v33, v21
	v_pk_mov_b32 v[20:21], v[20:21], v[24:25] op_sel:[1,0]
	v_cvt_pk_bf16_f32 v10, v32, v10
	v_mov_b32_e32 v32, v24
	v_pk_mul_f32 v[20:21], v[30:31], v[20:21]
	v_cvt_pk_bf16_f32 v14, v19, v14
	s_nop 0
	v_sub_f32_e32 v11, v20, v21
	v_pk_mul_f32 v[20:21], v[30:31], v[32:33]
	s_nop 0
	v_add_f32_e32 v19, v20, v21
	v_pk_mul_f32 v[20:21], v[28:29], v[26:27] op_sel:[1,1] op_sel_hi:[0,1]
	v_pk_fma_f32 v[24:25], v[28:29], v[22:23], v[20:21] op_sel:[0,1,0]
	v_pk_fma_f32 v[20:21], v[28:29], v[22:23], v[20:21] op_sel:[0,1,0] neg_lo:[0,0,1] neg_hi:[0,0,1]
	v_mov_b32_e32 v22, v24
	v_mov_b32_e32 v23, v21
	v_pk_mov_b32 v[20:21], v[20:21], v[24:25] op_sel:[1,0]
	s_nop 0
	v_pk_mul_f32 v[20:21], v[30:31], v[20:21]
	s_nop 0
	v_sub_f32_e32 v15, v20, v21
	v_pk_mul_f32 v[20:21], v[30:31], v[22:23]
	v_cvt_pk_bf16_f32 v15, v11, v15
	s_nop 0
	v_add_f32_e32 v20, v20, v21
	v_cvt_pk_bf16_f32 v11, v19, v20
	v_ashrrev_i32_e32 v19, 31, v18
	v_lshlrev_b64 v[20:21], 10, v[18:19]
	v_or_b32_e32 v18, 1, v18
	v_ashrrev_i32_e32 v19, 31, v18
	v_lshl_add_u64 v[20:21], s[0:1], 0, v[20:21]
	v_lshlrev_b64 v[18:19], 10, v[18:19]
	v_lshl_add_u64 v[16:17], v[20:21], 0, v[40:41]
	v_lshl_add_u64 v[18:19], s[0:1], 0, v[18:19]
	v_lshl_add_u64 v[18:19], v[18:19], 0, v[40:41]
	global_store_dwordx4 v[16:17], v[4:7], off
	global_store_dwordx4 v[16:17], v[12:15], off offset:16
	global_store_dwordx4 v[18:19], v[0:3], off
	global_store_dwordx4 v[18:19], v[8:11], off offset:16
	s_cbranch_scc1 .LBB0_1199
